# P0 adaLN mat-vec loop unrolled with 15-trip-deep weight prefetch ring (was 32 exposed round trips per unit)
# speedup vs baseline: 1.0084x; 1.0083x over previous
.LBB0_36:
	v_and_b32_e32 v4, 0x3ff, v3
	v_mov_b32_e32 v5, s66
	v_mov_b32_e32 v23, s65
	v_cmp_gt_u32_e32 vcc, s64, v3
	s_nop 1
	v_cndmask_b32_e32 v8, v4, v3, vcc
	v_cndmask_b32_e32 v4, v5, v23, vcc
	ds_read_b64 v[4:5], v4
	v_cmp_lt_u32_e32 vcc, s71, v3
	s_or_b64 s[52:53], vcc, s[52:53]
	s_waitcnt lgkmcnt(0)
	v_lshl_add_u64 v[4:5], v[8:9], 2, v[4:5]
	flat_load_dword v4, v[4:5]
	v_add_u32_e32 v5, 0x100, v3
	v_mov_b32_e32 v3, v5
	s_waitcnt vmcnt(0) lgkmcnt(0)
	v_mul_f32_e32 v5, 0xbfb8aa3b, v4
	v_fma_f32 v8, v4, s67, -v5
	v_rndne_f32_e32 v23, v5
	v_fmac_f32_e32 v8, 0xb2a5705f, v4
	v_sub_f32_e32 v5, v5, v23
	v_add_f32_e32 v5, v5, v8
	v_cvt_i32_f32_e32 v23, v23
	v_exp_f32_e32 v5, v5
	v_cmp_nlt_f32_e32 vcc, s68, v4
	v_ldexp_f32 v5, v5, v23
	s_nop 0
	v_cndmask_b32_e32 v5, 0, v5, vcc
	v_cmp_ngt_f32_e32 vcc, s69, v4
	s_nop 1
	v_cndmask_b32_e32 v5, v95, v5, vcc
	v_add_f32_e32 v5, 1.0, v5
	v_div_scale_f32 v8, s[54:55], v5, v5, v4
	v_rcp_f32_e32 v23, v8
	v_div_scale_f32 v61, vcc, v4, v5, v4
	v_fma_f32 v65, -v8, v23, 1.0
	v_fmac_f32_e32 v23, v65, v23
	v_mul_f32_e32 v65, v61, v23
	v_fma_f32 v66, -v8, v65, v61
	v_fmac_f32_e32 v65, v66, v23
	v_fma_f32 v8, -v8, v65, v61
	v_div_fmas_f32 v8, v8, v23, v65
	v_div_fixup_f32 v4, v8, v5, v4
	ds_write_b32 v2, v4
	v_add_u32_e32 v2, 0x400, v2
	s_andn2_b64 exec, exec, s[52:53]
	s_cbranch_execnz .LBB0_36
	s_or_b64 exec, exec, s[52:53]
	v_mov_b32_e32 v2, s72
	s_waitcnt lgkmcnt(0)
	s_barrier
	ds_read_b64 v[2:3], v2
	v_mov_b32_e32 v61, v9
	v_mov_b32_e32 v4, 0
	s_mov_b64 s[52:53], 0
	v_mov_b32_e32 v8, v81
	s_waitcnt lgkmcnt(0)
	v_add_co_u32_e32 v2, vcc, v2, v10
	v_addc_co_u32_e32 v3, vcc, v3, v11, vcc
	v_lshl_add_u64 v[2:3], v[60:61], 2, v[2:3]
	v_mov_b32_e32 v5, v4
	v_mov_b32_e32 v68, v4
	v_mov_b32_e32 v69, v4
	v_mov_b32_e32 v70, v4
	v_mov_b32_e32 v71, v4
	v_mov_b32_e32 v72, v4
	v_mov_b32_e32 v73, v4
	v_mov_b32_e32 v23, v4
	v_mov_b32_e32 v210, v2
	v_mov_b32_e32 v211, v3
	global_load_dword v150, v[210:211], off
	v_add_co_u32_e32 v210, vcc, 0x6000, v210
	v_addc_co_u32_e32 v211, vcc, 0, v211, vcc
	global_load_dword v151, v[210:211], off
	v_add_co_u32_e32 v210, vcc, 0x6000, v210
	v_addc_co_u32_e32 v211, vcc, 0, v211, vcc
	global_load_dword v152, v[210:211], off
	v_add_co_u32_e32 v210, vcc, 0x6000, v210
	v_addc_co_u32_e32 v211, vcc, 0, v211, vcc
	global_load_dword v153, v[210:211], off
	v_add_co_u32_e32 v210, vcc, 0x6000, v210
	v_addc_co_u32_e32 v211, vcc, 0, v211, vcc
	global_load_dword v154, v[210:211], off
	v_add_co_u32_e32 v210, vcc, 0x6000, v210
	v_addc_co_u32_e32 v211, vcc, 0, v211, vcc
	global_load_dword v155, v[210:211], off
	v_add_co_u32_e32 v210, vcc, 0x6000, v210
	v_addc_co_u32_e32 v211, vcc, 0, v211, vcc
	global_load_dword v156, v[210:211], off
	v_add_co_u32_e32 v210, vcc, 0x6000, v210
	v_addc_co_u32_e32 v211, vcc, 0, v211, vcc
	global_load_dword v157, v[210:211], off
	v_add_co_u32_e32 v210, vcc, 0x6000, v210
	v_addc_co_u32_e32 v211, vcc, 0, v211, vcc
	global_load_dword v158, v[210:211], off
	v_add_co_u32_e32 v210, vcc, 0x6000, v210
	v_addc_co_u32_e32 v211, vcc, 0, v211, vcc
	global_load_dword v159, v[210:211], off
	v_add_co_u32_e32 v210, vcc, 0x6000, v210
	v_addc_co_u32_e32 v211, vcc, 0, v211, vcc
	global_load_dword v160, v[210:211], off
	v_add_co_u32_e32 v210, vcc, 0x6000, v210
	v_addc_co_u32_e32 v211, vcc, 0, v211, vcc
	global_load_dword v161, v[210:211], off
	v_add_co_u32_e32 v210, vcc, 0x6000, v210
	v_addc_co_u32_e32 v211, vcc, 0, v211, vcc
	global_load_dword v162, v[210:211], off
	v_add_co_u32_e32 v210, vcc, 0x6000, v210
	v_addc_co_u32_e32 v211, vcc, 0, v211, vcc
	global_load_dword v163, v[210:211], off
	v_add_co_u32_e32 v210, vcc, 0x6000, v210
	v_addc_co_u32_e32 v211, vcc, 0, v211, vcc
	global_load_dword v164, v[210:211], off
	v_add_co_u32_e32 v210, vcc, 0x6000, v210
	v_addc_co_u32_e32 v211, vcc, 0, v211, vcc
	global_load_dword v165, v[210:211], off
	v_add_co_u32_e32 v210, vcc, 0x6000, v210
	v_addc_co_u32_e32 v211, vcc, 0, v211, vcc
	global_load_dword v166, v[210:211], off
	v_add_co_u32_e32 v210, vcc, 0x6000, v210
	v_addc_co_u32_e32 v211, vcc, 0, v211, vcc
	global_load_dword v167, v[210:211], off
	v_add_co_u32_e32 v210, vcc, 0x6000, v210
	v_addc_co_u32_e32 v211, vcc, 0, v211, vcc
	global_load_dword v168, v[210:211], off
	v_add_co_u32_e32 v210, vcc, 0x6000, v210
	v_addc_co_u32_e32 v211, vcc, 0, v211, vcc
	global_load_dword v169, v[210:211], off
	v_add_co_u32_e32 v210, vcc, 0x6000, v210
	v_addc_co_u32_e32 v211, vcc, 0, v211, vcc
	global_load_dword v170, v[210:211], off
	v_add_co_u32_e32 v210, vcc, 0x6000, v210
	v_addc_co_u32_e32 v211, vcc, 0, v211, vcc
	global_load_dword v171, v[210:211], off
	v_add_co_u32_e32 v210, vcc, 0x6000, v210
	v_addc_co_u32_e32 v211, vcc, 0, v211, vcc
	global_load_dword v172, v[210:211], off
	v_add_co_u32_e32 v210, vcc, 0x6000, v210
	v_addc_co_u32_e32 v211, vcc, 0, v211, vcc
	global_load_dword v173, v[210:211], off
	v_add_co_u32_e32 v210, vcc, 0x6000, v210
	v_addc_co_u32_e32 v211, vcc, 0, v211, vcc
	global_load_dword v174, v[210:211], off
	v_add_co_u32_e32 v210, vcc, 0x6000, v210
	v_addc_co_u32_e32 v211, vcc, 0, v211, vcc
	global_load_dword v175, v[210:211], off
	v_add_co_u32_e32 v210, vcc, 0x6000, v210
	v_addc_co_u32_e32 v211, vcc, 0, v211, vcc
	global_load_dword v176, v[210:211], off
	v_add_co_u32_e32 v210, vcc, 0x6000, v210
	v_addc_co_u32_e32 v211, vcc, 0, v211, vcc
	global_load_dword v177, v[210:211], off
	v_add_co_u32_e32 v210, vcc, 0x6000, v210
	v_addc_co_u32_e32 v211, vcc, 0, v211, vcc
	global_load_dword v178, v[210:211], off
	v_add_co_u32_e32 v210, vcc, 0x6000, v210
	v_addc_co_u32_e32 v211, vcc, 0, v211, vcc
	global_load_dword v179, v[210:211], off
	v_add_co_u32_e32 v210, vcc, 0x6000, v210
	v_addc_co_u32_e32 v211, vcc, 0, v211, vcc
	global_load_dword v180, v[210:211], off
	v_add_co_u32_e32 v210, vcc, 0x6000, v210
	v_addc_co_u32_e32 v211, vcc, 0, v211, vcc
	global_load_dword v181, v[210:211], off
	v_add_co_u32_e32 v210, vcc, 0x6000, v210
	v_addc_co_u32_e32 v211, vcc, 0, v211, vcc
	global_load_dword v182, v[210:211], off
	v_add_co_u32_e32 v210, vcc, 0x6000, v210
	v_addc_co_u32_e32 v211, vcc, 0, v211, vcc
	global_load_dword v183, v[210:211], off
	v_add_co_u32_e32 v210, vcc, 0x6000, v210
	v_addc_co_u32_e32 v211, vcc, 0, v211, vcc
	global_load_dword v184, v[210:211], off
	v_add_co_u32_e32 v210, vcc, 0x6000, v210
	v_addc_co_u32_e32 v211, vcc, 0, v211, vcc
	global_load_dword v185, v[210:211], off
	v_add_co_u32_e32 v210, vcc, 0x6000, v210
	v_addc_co_u32_e32 v211, vcc, 0, v211, vcc
	global_load_dword v186, v[210:211], off
	v_add_co_u32_e32 v210, vcc, 0x6000, v210
	v_addc_co_u32_e32 v211, vcc, 0, v211, vcc
	global_load_dword v187, v[210:211], off
	v_add_co_u32_e32 v210, vcc, 0x6000, v210
	v_addc_co_u32_e32 v211, vcc, 0, v211, vcc
	global_load_dword v188, v[210:211], off
	v_add_co_u32_e32 v210, vcc, 0x6000, v210
	v_addc_co_u32_e32 v211, vcc, 0, v211, vcc
	global_load_dword v189, v[210:211], off
	v_add_co_u32_e32 v210, vcc, 0x6000, v210
	v_addc_co_u32_e32 v211, vcc, 0, v211, vcc
	global_load_dword v190, v[210:211], off
	v_add_co_u32_e32 v210, vcc, 0x6000, v210
	v_addc_co_u32_e32 v211, vcc, 0, v211, vcc
	global_load_dword v191, v[210:211], off
	v_add_co_u32_e32 v210, vcc, 0x6000, v210
	v_addc_co_u32_e32 v211, vcc, 0, v211, vcc
	global_load_dword v192, v[210:211], off
	v_add_co_u32_e32 v210, vcc, 0x6000, v210
	v_addc_co_u32_e32 v211, vcc, 0, v211, vcc
	global_load_dword v193, v[210:211], off
	v_add_co_u32_e32 v210, vcc, 0x6000, v210
	v_addc_co_u32_e32 v211, vcc, 0, v211, vcc
	global_load_dword v194, v[210:211], off
	v_add_co_u32_e32 v210, vcc, 0x6000, v210
	v_addc_co_u32_e32 v211, vcc, 0, v211, vcc
	global_load_dword v195, v[210:211], off
	v_add_co_u32_e32 v210, vcc, 0x6000, v210
	v_addc_co_u32_e32 v211, vcc, 0, v211, vcc
	global_load_dword v196, v[210:211], off
	v_add_co_u32_e32 v210, vcc, 0x6000, v210
	v_addc_co_u32_e32 v211, vcc, 0, v211, vcc
	global_load_dword v197, v[210:211], off
	v_add_co_u32_e32 v210, vcc, 0x6000, v210
	v_addc_co_u32_e32 v211, vcc, 0, v211, vcc
	global_load_dword v198, v[210:211], off
	v_add_co_u32_e32 v210, vcc, 0x6000, v210
	v_addc_co_u32_e32 v211, vcc, 0, v211, vcc
	global_load_dword v199, v[210:211], off
	v_add_co_u32_e32 v210, vcc, 0x6000, v210
	v_addc_co_u32_e32 v211, vcc, 0, v211, vcc
	global_load_dword v200, v[210:211], off
	v_add_co_u32_e32 v210, vcc, 0x6000, v210
	v_addc_co_u32_e32 v211, vcc, 0, v211, vcc
	global_load_dword v201, v[210:211], off
	v_add_co_u32_e32 v210, vcc, 0x6000, v210
	v_addc_co_u32_e32 v211, vcc, 0, v211, vcc
	global_load_dword v202, v[210:211], off
	v_add_co_u32_e32 v210, vcc, 0x6000, v210
	v_addc_co_u32_e32 v211, vcc, 0, v211, vcc
	global_load_dword v203, v[210:211], off
	v_add_co_u32_e32 v210, vcc, 0x6000, v210
	v_addc_co_u32_e32 v211, vcc, 0, v211, vcc
	global_load_dword v204, v[210:211], off
	v_add_co_u32_e32 v210, vcc, 0x6000, v210
	v_addc_co_u32_e32 v211, vcc, 0, v211, vcc
	global_load_dword v205, v[210:211], off
	v_add_co_u32_e32 v210, vcc, 0x6000, v210
	v_addc_co_u32_e32 v211, vcc, 0, v211, vcc
	global_load_dword v206, v[210:211], off
	v_add_co_u32_e32 v210, vcc, 0x6000, v210
	v_addc_co_u32_e32 v211, vcc, 0, v211, vcc
	global_load_dword v207, v[210:211], off
	v_add_co_u32_e32 v210, vcc, 0x6000, v210
	v_addc_co_u32_e32 v211, vcc, 0, v211, vcc
	global_load_dword v208, v[210:211], off
	v_add_co_u32_e32 v210, vcc, 0x6000, v210
	v_addc_co_u32_e32 v211, vcc, 0, v211, vcc
	global_load_dword v209, v[210:211], off
	v_add_co_u32_e32 v210, vcc, 0x6000, v210
	v_addc_co_u32_e32 v211, vcc, 0, v211, vcc
	ds_read_b128 v[98:101], v8 offset:4096
	ds_read_b128 v[102:105], v8 offset:8192
	ds_read_b128 v[106:109], v8 offset:12288
	ds_read_b128 v[110:113], v8 offset:16384
	ds_read_b128 v[114:117], v8 offset:20480
	ds_read_b128 v[118:121], v8 offset:24576
	ds_read_b128 v[122:125], v8 offset:28672
	ds_read_b128 v[126:129], v8
	ds_read_b128 v[134:137], v8 offset:32768
	s_waitcnt lgkmcnt(0)
	v_mov_b32_e32 v143, v98
	v_mov_b32_e32 v144, v102
	v_mov_b32_e32 v145, v106
	v_mov_b32_e32 v142, v126
	v_mov_b32_e32 v146, v110
	v_mov_b32_e32 v147, v114
	v_mov_b32_e32 v148, v118
	v_mov_b32_e32 v149, v122
	v_mov_b32_e32 v98, v127
	v_mov_b32_e32 v106, v103
	v_mov_b32_e32 v114, v111
	v_mov_b32_e32 v122, v119
	v_mov_b32_e32 v102, v128
	v_mov_b32_e32 v103, v100
	v_mov_b32_e32 v110, v104
	v_mov_b32_e32 v111, v108
	v_mov_b32_e32 v118, v112
	v_mov_b32_e32 v119, v116
	v_mov_b32_e32 v126, v120
	v_mov_b32_e32 v127, v124
	v_mov_b32_e32 v100, v129
	v_mov_b32_e32 v108, v105
	v_mov_b32_e32 v116, v113
	v_mov_b32_e32 v124, v121
	v_add_u32_e32 v8, 16, v8
	s_waitcnt vmcnt(56)
	v_mov_b32_e32 v66, v150
	v_mov_b32_e32 v130, v151
	v_mov_b32_e32 v138, v152
	v_mov_b32_e32 v140, v153
	global_load_dword v150, v[210:211], off
	v_add_co_u32_e32 v210, vcc, 0x6000, v210
	v_addc_co_u32_e32 v211, vcc, 0, v211, vcc
	global_load_dword v151, v[210:211], off
	v_add_co_u32_e32 v210, vcc, 0x6000, v210
	v_addc_co_u32_e32 v211, vcc, 0, v211, vcc
	global_load_dword v152, v[210:211], off
	v_add_co_u32_e32 v210, vcc, 0x6000, v210
	v_addc_co_u32_e32 v211, vcc, 0, v211, vcc
	global_load_dword v153, v[210:211], off
	v_add_co_u32_e32 v210, vcc, 0x6000, v210
	v_addc_co_u32_e32 v211, vcc, 0, v211, vcc
	v_pk_fma_f32 v[4:5], v[66:67], v[142:143], v[4:5] op_sel_hi:[0,1,1]
	v_pk_fma_f32 v[68:69], v[66:67], v[144:145], v[68:69] op_sel_hi:[0,1,1]
	v_pk_fma_f32 v[70:71], v[66:67], v[146:147], v[70:71] op_sel_hi:[0,1,1]
	v_pk_fma_f32 v[72:73], v[66:67], v[148:149], v[72:73] op_sel_hi:[0,1,1]
	v_fmac_f32_e32 v23, v66, v134
	v_pk_fma_f32 v[4:5], v[130:131], v[98:99], v[4:5] op_sel_hi:[0,1,1]
	v_pk_fma_f32 v[68:69], v[130:131], v[106:107], v[68:69] op_sel_hi:[0,1,1]
	v_pk_fma_f32 v[70:71], v[130:131], v[114:115], v[70:71] op_sel_hi:[0,1,1]
	v_pk_fma_f32 v[72:73], v[130:131], v[122:123], v[72:73] op_sel_hi:[0,1,1]
	v_fmac_f32_e32 v23, v130, v135
	v_pk_fma_f32 v[4:5], v[138:139], v[102:103], v[4:5] op_sel_hi:[0,1,1]
	v_pk_fma_f32 v[68:69], v[138:139], v[110:111], v[68:69] op_sel_hi:[0,1,1]
	v_pk_fma_f32 v[70:71], v[138:139], v[118:119], v[70:71] op_sel_hi:[0,1,1]
	v_pk_fma_f32 v[72:73], v[138:139], v[126:127], v[72:73] op_sel_hi:[0,1,1]
	v_fmac_f32_e32 v23, v138, v136
	v_pk_fma_f32 v[4:5], v[140:141], v[100:101], v[4:5] op_sel_hi:[0,1,1]
	v_pk_fma_f32 v[68:69], v[140:141], v[108:109], v[68:69] op_sel_hi:[0,1,1]
	v_pk_fma_f32 v[70:71], v[140:141], v[116:117], v[70:71] op_sel_hi:[0,1,1]
	v_pk_fma_f32 v[72:73], v[140:141], v[124:125], v[72:73] op_sel_hi:[0,1,1]
	v_fmac_f32_e32 v23, v140, v137
	ds_read_b128 v[98:101], v8 offset:4096
	ds_read_b128 v[102:105], v8 offset:8192
	ds_read_b128 v[106:109], v8 offset:12288
	ds_read_b128 v[110:113], v8 offset:16384
	ds_read_b128 v[114:117], v8 offset:20480
	ds_read_b128 v[118:121], v8 offset:24576
	ds_read_b128 v[122:125], v8 offset:28672
	ds_read_b128 v[126:129], v8
	ds_read_b128 v[134:137], v8 offset:32768
	s_waitcnt lgkmcnt(0)
	v_mov_b32_e32 v143, v98
	v_mov_b32_e32 v144, v102
	v_mov_b32_e32 v145, v106
	v_mov_b32_e32 v142, v126
	v_mov_b32_e32 v146, v110
	v_mov_b32_e32 v147, v114
	v_mov_b32_e32 v148, v118
	v_mov_b32_e32 v149, v122
	v_mov_b32_e32 v98, v127
	v_mov_b32_e32 v106, v103
	v_mov_b32_e32 v114, v111
	v_mov_b32_e32 v122, v119
	v_mov_b32_e32 v102, v128
	v_mov_b32_e32 v103, v100
	v_mov_b32_e32 v110, v104
	v_mov_b32_e32 v111, v108
	v_mov_b32_e32 v118, v112
	v_mov_b32_e32 v119, v116
	v_mov_b32_e32 v126, v120
	v_mov_b32_e32 v127, v124
	v_mov_b32_e32 v100, v129
	v_mov_b32_e32 v108, v105
	v_mov_b32_e32 v116, v113
	v_mov_b32_e32 v124, v121
	v_add_u32_e32 v8, 16, v8
	s_waitcnt vmcnt(56)
	v_mov_b32_e32 v66, v154
	v_mov_b32_e32 v130, v155
	v_mov_b32_e32 v138, v156
	v_mov_b32_e32 v140, v157
	global_load_dword v154, v[210:211], off
	v_add_co_u32_e32 v210, vcc, 0x6000, v210
	v_addc_co_u32_e32 v211, vcc, 0, v211, vcc
	global_load_dword v155, v[210:211], off
	v_add_co_u32_e32 v210, vcc, 0x6000, v210
	v_addc_co_u32_e32 v211, vcc, 0, v211, vcc
	global_load_dword v156, v[210:211], off
	v_add_co_u32_e32 v210, vcc, 0x6000, v210
	v_addc_co_u32_e32 v211, vcc, 0, v211, vcc
	global_load_dword v157, v[210:211], off
	v_add_co_u32_e32 v210, vcc, 0x6000, v210
	v_addc_co_u32_e32 v211, vcc, 0, v211, vcc
	v_pk_fma_f32 v[4:5], v[66:67], v[142:143], v[4:5] op_sel_hi:[0,1,1]
	v_pk_fma_f32 v[68:69], v[66:67], v[144:145], v[68:69] op_sel_hi:[0,1,1]
	v_pk_fma_f32 v[70:71], v[66:67], v[146:147], v[70:71] op_sel_hi:[0,1,1]
	v_pk_fma_f32 v[72:73], v[66:67], v[148:149], v[72:73] op_sel_hi:[0,1,1]
	v_fmac_f32_e32 v23, v66, v134
	v_pk_fma_f32 v[4:5], v[130:131], v[98:99], v[4:5] op_sel_hi:[0,1,1]
	v_pk_fma_f32 v[68:69], v[130:131], v[106:107], v[68:69] op_sel_hi:[0,1,1]
	v_pk_fma_f32 v[70:71], v[130:131], v[114:115], v[70:71] op_sel_hi:[0,1,1]
	v_pk_fma_f32 v[72:73], v[130:131], v[122:123], v[72:73] op_sel_hi:[0,1,1]
	v_fmac_f32_e32 v23, v130, v135
	v_pk_fma_f32 v[4:5], v[138:139], v[102:103], v[4:5] op_sel_hi:[0,1,1]
	v_pk_fma_f32 v[68:69], v[138:139], v[110:111], v[68:69] op_sel_hi:[0,1,1]
	v_pk_fma_f32 v[70:71], v[138:139], v[118:119], v[70:71] op_sel_hi:[0,1,1]
	v_pk_fma_f32 v[72:73], v[138:139], v[126:127], v[72:73] op_sel_hi:[0,1,1]
	v_fmac_f32_e32 v23, v138, v136
	v_pk_fma_f32 v[4:5], v[140:141], v[100:101], v[4:5] op_sel_hi:[0,1,1]
	v_pk_fma_f32 v[68:69], v[140:141], v[108:109], v[68:69] op_sel_hi:[0,1,1]
	v_pk_fma_f32 v[70:71], v[140:141], v[116:117], v[70:71] op_sel_hi:[0,1,1]
	v_pk_fma_f32 v[72:73], v[140:141], v[124:125], v[72:73] op_sel_hi:[0,1,1]
	v_fmac_f32_e32 v23, v140, v137
	ds_read_b128 v[98:101], v8 offset:4096
	ds_read_b128 v[102:105], v8 offset:8192
	ds_read_b128 v[106:109], v8 offset:12288
	ds_read_b128 v[110:113], v8 offset:16384
	ds_read_b128 v[114:117], v8 offset:20480
	ds_read_b128 v[118:121], v8 offset:24576
	ds_read_b128 v[122:125], v8 offset:28672
	ds_read_b128 v[126:129], v8
	ds_read_b128 v[134:137], v8 offset:32768
	s_waitcnt lgkmcnt(0)
	v_mov_b32_e32 v143, v98
	v_mov_b32_e32 v144, v102
	v_mov_b32_e32 v145, v106
	v_mov_b32_e32 v142, v126
	v_mov_b32_e32 v146, v110
	v_mov_b32_e32 v147, v114
	v_mov_b32_e32 v148, v118
	v_mov_b32_e32 v149, v122
	v_mov_b32_e32 v98, v127
	v_mov_b32_e32 v106, v103
	v_mov_b32_e32 v114, v111
	v_mov_b32_e32 v122, v119
	v_mov_b32_e32 v102, v128
	v_mov_b32_e32 v103, v100
	v_mov_b32_e32 v110, v104
	v_mov_b32_e32 v111, v108
	v_mov_b32_e32 v118, v112
	v_mov_b32_e32 v119, v116
	v_mov_b32_e32 v126, v120
	v_mov_b32_e32 v127, v124
	v_mov_b32_e32 v100, v129
	v_mov_b32_e32 v108, v105
	v_mov_b32_e32 v116, v113
	v_mov_b32_e32 v124, v121
	v_add_u32_e32 v8, 16, v8
	s_waitcnt vmcnt(56)
	v_mov_b32_e32 v66, v158
	v_mov_b32_e32 v130, v159
	v_mov_b32_e32 v138, v160
	v_mov_b32_e32 v140, v161
	global_load_dword v158, v[210:211], off
	v_add_co_u32_e32 v210, vcc, 0x6000, v210
	v_addc_co_u32_e32 v211, vcc, 0, v211, vcc
	global_load_dword v159, v[210:211], off
	v_add_co_u32_e32 v210, vcc, 0x6000, v210
	v_addc_co_u32_e32 v211, vcc, 0, v211, vcc
	global_load_dword v160, v[210:211], off
	v_add_co_u32_e32 v210, vcc, 0x6000, v210
	v_addc_co_u32_e32 v211, vcc, 0, v211, vcc
	global_load_dword v161, v[210:211], off
	v_add_co_u32_e32 v210, vcc, 0x6000, v210
	v_addc_co_u32_e32 v211, vcc, 0, v211, vcc
	v_pk_fma_f32 v[4:5], v[66:67], v[142:143], v[4:5] op_sel_hi:[0,1,1]
	v_pk_fma_f32 v[68:69], v[66:67], v[144:145], v[68:69] op_sel_hi:[0,1,1]
	v_pk_fma_f32 v[70:71], v[66:67], v[146:147], v[70:71] op_sel_hi:[0,1,1]
	v_pk_fma_f32 v[72:73], v[66:67], v[148:149], v[72:73] op_sel_hi:[0,1,1]
	v_fmac_f32_e32 v23, v66, v134
	v_pk_fma_f32 v[4:5], v[130:131], v[98:99], v[4:5] op_sel_hi:[0,1,1]
	v_pk_fma_f32 v[68:69], v[130:131], v[106:107], v[68:69] op_sel_hi:[0,1,1]
	v_pk_fma_f32 v[70:71], v[130:131], v[114:115], v[70:71] op_sel_hi:[0,1,1]
	v_pk_fma_f32 v[72:73], v[130:131], v[122:123], v[72:73] op_sel_hi:[0,1,1]
	v_fmac_f32_e32 v23, v130, v135
	v_pk_fma_f32 v[4:5], v[138:139], v[102:103], v[4:5] op_sel_hi:[0,1,1]
	v_pk_fma_f32 v[68:69], v[138:139], v[110:111], v[68:69] op_sel_hi:[0,1,1]
	v_pk_fma_f32 v[70:71], v[138:139], v[118:119], v[70:71] op_sel_hi:[0,1,1]
	v_pk_fma_f32 v[72:73], v[138:139], v[126:127], v[72:73] op_sel_hi:[0,1,1]
	v_fmac_f32_e32 v23, v138, v136
	v_pk_fma_f32 v[4:5], v[140:141], v[100:101], v[4:5] op_sel_hi:[0,1,1]
	v_pk_fma_f32 v[68:69], v[140:141], v[108:109], v[68:69] op_sel_hi:[0,1,1]
	v_pk_fma_f32 v[70:71], v[140:141], v[116:117], v[70:71] op_sel_hi:[0,1,1]
	v_pk_fma_f32 v[72:73], v[140:141], v[124:125], v[72:73] op_sel_hi:[0,1,1]
	v_fmac_f32_e32 v23, v140, v137
	ds_read_b128 v[98:101], v8 offset:4096
	ds_read_b128 v[102:105], v8 offset:8192
	ds_read_b128 v[106:109], v8 offset:12288
	ds_read_b128 v[110:113], v8 offset:16384
	ds_read_b128 v[114:117], v8 offset:20480
	ds_read_b128 v[118:121], v8 offset:24576
	ds_read_b128 v[122:125], v8 offset:28672
	ds_read_b128 v[126:129], v8
	ds_read_b128 v[134:137], v8 offset:32768
	s_waitcnt lgkmcnt(0)
	v_mov_b32_e32 v143, v98
	v_mov_b32_e32 v144, v102
	v_mov_b32_e32 v145, v106
	v_mov_b32_e32 v142, v126
	v_mov_b32_e32 v146, v110
	v_mov_b32_e32 v147, v114
	v_mov_b32_e32 v148, v118
	v_mov_b32_e32 v149, v122
	v_mov_b32_e32 v98, v127
	v_mov_b32_e32 v106, v103
	v_mov_b32_e32 v114, v111
	v_mov_b32_e32 v122, v119
	v_mov_b32_e32 v102, v128
	v_mov_b32_e32 v103, v100
	v_mov_b32_e32 v110, v104
	v_mov_b32_e32 v111, v108
	v_mov_b32_e32 v118, v112
	v_mov_b32_e32 v119, v116
	v_mov_b32_e32 v126, v120
	v_mov_b32_e32 v127, v124
	v_mov_b32_e32 v100, v129
	v_mov_b32_e32 v108, v105
	v_mov_b32_e32 v116, v113
	v_mov_b32_e32 v124, v121
	v_add_u32_e32 v8, 16, v8
	s_waitcnt vmcnt(56)
	v_mov_b32_e32 v66, v162
	v_mov_b32_e32 v130, v163
	v_mov_b32_e32 v138, v164
	v_mov_b32_e32 v140, v165
	global_load_dword v162, v[210:211], off
	v_add_co_u32_e32 v210, vcc, 0x6000, v210
	v_addc_co_u32_e32 v211, vcc, 0, v211, vcc
	global_load_dword v163, v[210:211], off
	v_add_co_u32_e32 v210, vcc, 0x6000, v210
	v_addc_co_u32_e32 v211, vcc, 0, v211, vcc
	global_load_dword v164, v[210:211], off
	v_add_co_u32_e32 v210, vcc, 0x6000, v210
	v_addc_co_u32_e32 v211, vcc, 0, v211, vcc
	global_load_dword v165, v[210:211], off
	v_add_co_u32_e32 v210, vcc, 0x6000, v210
	v_addc_co_u32_e32 v211, vcc, 0, v211, vcc
	v_pk_fma_f32 v[4:5], v[66:67], v[142:143], v[4:5] op_sel_hi:[0,1,1]
	v_pk_fma_f32 v[68:69], v[66:67], v[144:145], v[68:69] op_sel_hi:[0,1,1]
	v_pk_fma_f32 v[70:71], v[66:67], v[146:147], v[70:71] op_sel_hi:[0,1,1]
	v_pk_fma_f32 v[72:73], v[66:67], v[148:149], v[72:73] op_sel_hi:[0,1,1]
	v_fmac_f32_e32 v23, v66, v134
	v_pk_fma_f32 v[4:5], v[130:131], v[98:99], v[4:5] op_sel_hi:[0,1,1]
	v_pk_fma_f32 v[68:69], v[130:131], v[106:107], v[68:69] op_sel_hi:[0,1,1]
	v_pk_fma_f32 v[70:71], v[130:131], v[114:115], v[70:71] op_sel_hi:[0,1,1]
	v_pk_fma_f32 v[72:73], v[130:131], v[122:123], v[72:73] op_sel_hi:[0,1,1]
	v_fmac_f32_e32 v23, v130, v135
	v_pk_fma_f32 v[4:5], v[138:139], v[102:103], v[4:5] op_sel_hi:[0,1,1]
	v_pk_fma_f32 v[68:69], v[138:139], v[110:111], v[68:69] op_sel_hi:[0,1,1]
	v_pk_fma_f32 v[70:71], v[138:139], v[118:119], v[70:71] op_sel_hi:[0,1,1]
	v_pk_fma_f32 v[72:73], v[138:139], v[126:127], v[72:73] op_sel_hi:[0,1,1]
	v_fmac_f32_e32 v23, v138, v136
	v_pk_fma_f32 v[4:5], v[140:141], v[100:101], v[4:5] op_sel_hi:[0,1,1]
	v_pk_fma_f32 v[68:69], v[140:141], v[108:109], v[68:69] op_sel_hi:[0,1,1]
	v_pk_fma_f32 v[70:71], v[140:141], v[116:117], v[70:71] op_sel_hi:[0,1,1]
	v_pk_fma_f32 v[72:73], v[140:141], v[124:125], v[72:73] op_sel_hi:[0,1,1]
	v_fmac_f32_e32 v23, v140, v137
	ds_read_b128 v[98:101], v8 offset:4096
	ds_read_b128 v[102:105], v8 offset:8192
	ds_read_b128 v[106:109], v8 offset:12288
	ds_read_b128 v[110:113], v8 offset:16384
	ds_read_b128 v[114:117], v8 offset:20480
	ds_read_b128 v[118:121], v8 offset:24576
	ds_read_b128 v[122:125], v8 offset:28672
	ds_read_b128 v[126:129], v8
	ds_read_b128 v[134:137], v8 offset:32768
	s_waitcnt lgkmcnt(0)
	v_mov_b32_e32 v143, v98
	v_mov_b32_e32 v144, v102
	v_mov_b32_e32 v145, v106
	v_mov_b32_e32 v142, v126
	v_mov_b32_e32 v146, v110
	v_mov_b32_e32 v147, v114
	v_mov_b32_e32 v148, v118
	v_mov_b32_e32 v149, v122
	v_mov_b32_e32 v98, v127
	v_mov_b32_e32 v106, v103
	v_mov_b32_e32 v114, v111
	v_mov_b32_e32 v122, v119
	v_mov_b32_e32 v102, v128
	v_mov_b32_e32 v103, v100
	v_mov_b32_e32 v110, v104
	v_mov_b32_e32 v111, v108
	v_mov_b32_e32 v118, v112
	v_mov_b32_e32 v119, v116
	v_mov_b32_e32 v126, v120
	v_mov_b32_e32 v127, v124
	v_mov_b32_e32 v100, v129
	v_mov_b32_e32 v108, v105
	v_mov_b32_e32 v116, v113
	v_mov_b32_e32 v124, v121
	v_add_u32_e32 v8, 16, v8
	s_waitcnt vmcnt(56)
	v_mov_b32_e32 v66, v166
	v_mov_b32_e32 v130, v167
	v_mov_b32_e32 v138, v168
	v_mov_b32_e32 v140, v169
	global_load_dword v166, v[210:211], off
	v_add_co_u32_e32 v210, vcc, 0x6000, v210
	v_addc_co_u32_e32 v211, vcc, 0, v211, vcc
	global_load_dword v167, v[210:211], off
	v_add_co_u32_e32 v210, vcc, 0x6000, v210
	v_addc_co_u32_e32 v211, vcc, 0, v211, vcc
	global_load_dword v168, v[210:211], off
	v_add_co_u32_e32 v210, vcc, 0x6000, v210
	v_addc_co_u32_e32 v211, vcc, 0, v211, vcc
	global_load_dword v169, v[210:211], off
	v_add_co_u32_e32 v210, vcc, 0x6000, v210
	v_addc_co_u32_e32 v211, vcc, 0, v211, vcc
	v_pk_fma_f32 v[4:5], v[66:67], v[142:143], v[4:5] op_sel_hi:[0,1,1]
	v_pk_fma_f32 v[68:69], v[66:67], v[144:145], v[68:69] op_sel_hi:[0,1,1]
	v_pk_fma_f32 v[70:71], v[66:67], v[146:147], v[70:71] op_sel_hi:[0,1,1]
	v_pk_fma_f32 v[72:73], v[66:67], v[148:149], v[72:73] op_sel_hi:[0,1,1]
	v_fmac_f32_e32 v23, v66, v134
	v_pk_fma_f32 v[4:5], v[130:131], v[98:99], v[4:5] op_sel_hi:[0,1,1]
	v_pk_fma_f32 v[68:69], v[130:131], v[106:107], v[68:69] op_sel_hi:[0,1,1]
	v_pk_fma_f32 v[70:71], v[130:131], v[114:115], v[70:71] op_sel_hi:[0,1,1]
	v_pk_fma_f32 v[72:73], v[130:131], v[122:123], v[72:73] op_sel_hi:[0,1,1]
	v_fmac_f32_e32 v23, v130, v135
	v_pk_fma_f32 v[4:5], v[138:139], v[102:103], v[4:5] op_sel_hi:[0,1,1]
	v_pk_fma_f32 v[68:69], v[138:139], v[110:111], v[68:69] op_sel_hi:[0,1,1]
	v_pk_fma_f32 v[70:71], v[138:139], v[118:119], v[70:71] op_sel_hi:[0,1,1]
	v_pk_fma_f32 v[72:73], v[138:139], v[126:127], v[72:73] op_sel_hi:[0,1,1]
	v_fmac_f32_e32 v23, v138, v136
	v_pk_fma_f32 v[4:5], v[140:141], v[100:101], v[4:5] op_sel_hi:[0,1,1]
	v_pk_fma_f32 v[68:69], v[140:141], v[108:109], v[68:69] op_sel_hi:[0,1,1]
	v_pk_fma_f32 v[70:71], v[140:141], v[116:117], v[70:71] op_sel_hi:[0,1,1]
	v_pk_fma_f32 v[72:73], v[140:141], v[124:125], v[72:73] op_sel_hi:[0,1,1]
	v_fmac_f32_e32 v23, v140, v137
	ds_read_b128 v[98:101], v8 offset:4096
	ds_read_b128 v[102:105], v8 offset:8192
	ds_read_b128 v[106:109], v8 offset:12288
	ds_read_b128 v[110:113], v8 offset:16384
	ds_read_b128 v[114:117], v8 offset:20480
	ds_read_b128 v[118:121], v8 offset:24576
	ds_read_b128 v[122:125], v8 offset:28672
	ds_read_b128 v[126:129], v8
	ds_read_b128 v[134:137], v8 offset:32768
	s_waitcnt lgkmcnt(0)
	v_mov_b32_e32 v143, v98
	v_mov_b32_e32 v144, v102
	v_mov_b32_e32 v145, v106
	v_mov_b32_e32 v142, v126
	v_mov_b32_e32 v146, v110
	v_mov_b32_e32 v147, v114
	v_mov_b32_e32 v148, v118
	v_mov_b32_e32 v149, v122
	v_mov_b32_e32 v98, v127
	v_mov_b32_e32 v106, v103
	v_mov_b32_e32 v114, v111
	v_mov_b32_e32 v122, v119
	v_mov_b32_e32 v102, v128
	v_mov_b32_e32 v103, v100
	v_mov_b32_e32 v110, v104
	v_mov_b32_e32 v111, v108
	v_mov_b32_e32 v118, v112
	v_mov_b32_e32 v119, v116
	v_mov_b32_e32 v126, v120
	v_mov_b32_e32 v127, v124
	v_mov_b32_e32 v100, v129
	v_mov_b32_e32 v108, v105
	v_mov_b32_e32 v116, v113
	v_mov_b32_e32 v124, v121
	v_add_u32_e32 v8, 16, v8
	s_waitcnt vmcnt(56)
	v_mov_b32_e32 v66, v170
	v_mov_b32_e32 v130, v171
	v_mov_b32_e32 v138, v172
	v_mov_b32_e32 v140, v173
	global_load_dword v170, v[210:211], off
	v_add_co_u32_e32 v210, vcc, 0x6000, v210
	v_addc_co_u32_e32 v211, vcc, 0, v211, vcc
	global_load_dword v171, v[210:211], off
	v_add_co_u32_e32 v210, vcc, 0x6000, v210
	v_addc_co_u32_e32 v211, vcc, 0, v211, vcc
	global_load_dword v172, v[210:211], off
	v_add_co_u32_e32 v210, vcc, 0x6000, v210
	v_addc_co_u32_e32 v211, vcc, 0, v211, vcc
	global_load_dword v173, v[210:211], off
	v_add_co_u32_e32 v210, vcc, 0x6000, v210
	v_addc_co_u32_e32 v211, vcc, 0, v211, vcc
	v_pk_fma_f32 v[4:5], v[66:67], v[142:143], v[4:5] op_sel_hi:[0,1,1]
	v_pk_fma_f32 v[68:69], v[66:67], v[144:145], v[68:69] op_sel_hi:[0,1,1]
	v_pk_fma_f32 v[70:71], v[66:67], v[146:147], v[70:71] op_sel_hi:[0,1,1]
	v_pk_fma_f32 v[72:73], v[66:67], v[148:149], v[72:73] op_sel_hi:[0,1,1]
	v_fmac_f32_e32 v23, v66, v134
	v_pk_fma_f32 v[4:5], v[130:131], v[98:99], v[4:5] op_sel_hi:[0,1,1]
	v_pk_fma_f32 v[68:69], v[130:131], v[106:107], v[68:69] op_sel_hi:[0,1,1]
	v_pk_fma_f32 v[70:71], v[130:131], v[114:115], v[70:71] op_sel_hi:[0,1,1]
	v_pk_fma_f32 v[72:73], v[130:131], v[122:123], v[72:73] op_sel_hi:[0,1,1]
	v_fmac_f32_e32 v23, v130, v135
	v_pk_fma_f32 v[4:5], v[138:139], v[102:103], v[4:5] op_sel_hi:[0,1,1]
	v_pk_fma_f32 v[68:69], v[138:139], v[110:111], v[68:69] op_sel_hi:[0,1,1]
	v_pk_fma_f32 v[70:71], v[138:139], v[118:119], v[70:71] op_sel_hi:[0,1,1]
	v_pk_fma_f32 v[72:73], v[138:139], v[126:127], v[72:73] op_sel_hi:[0,1,1]
	v_fmac_f32_e32 v23, v138, v136
	v_pk_fma_f32 v[4:5], v[140:141], v[100:101], v[4:5] op_sel_hi:[0,1,1]
	v_pk_fma_f32 v[68:69], v[140:141], v[108:109], v[68:69] op_sel_hi:[0,1,1]
	v_pk_fma_f32 v[70:71], v[140:141], v[116:117], v[70:71] op_sel_hi:[0,1,1]
	v_pk_fma_f32 v[72:73], v[140:141], v[124:125], v[72:73] op_sel_hi:[0,1,1]
	v_fmac_f32_e32 v23, v140, v137
	ds_read_b128 v[98:101], v8 offset:4096
	ds_read_b128 v[102:105], v8 offset:8192
	ds_read_b128 v[106:109], v8 offset:12288
	ds_read_b128 v[110:113], v8 offset:16384
	ds_read_b128 v[114:117], v8 offset:20480
	ds_read_b128 v[118:121], v8 offset:24576
	ds_read_b128 v[122:125], v8 offset:28672
	ds_read_b128 v[126:129], v8
	ds_read_b128 v[134:137], v8 offset:32768
	s_waitcnt lgkmcnt(0)
	v_mov_b32_e32 v143, v98
	v_mov_b32_e32 v144, v102
	v_mov_b32_e32 v145, v106
	v_mov_b32_e32 v142, v126
	v_mov_b32_e32 v146, v110
	v_mov_b32_e32 v147, v114
	v_mov_b32_e32 v148, v118
	v_mov_b32_e32 v149, v122
	v_mov_b32_e32 v98, v127
	v_mov_b32_e32 v106, v103
	v_mov_b32_e32 v114, v111
	v_mov_b32_e32 v122, v119
	v_mov_b32_e32 v102, v128
	v_mov_b32_e32 v103, v100
	v_mov_b32_e32 v110, v104
	v_mov_b32_e32 v111, v108
	v_mov_b32_e32 v118, v112
	v_mov_b32_e32 v119, v116
	v_mov_b32_e32 v126, v120
	v_mov_b32_e32 v127, v124
	v_mov_b32_e32 v100, v129
	v_mov_b32_e32 v108, v105
	v_mov_b32_e32 v116, v113
	v_mov_b32_e32 v124, v121
	v_add_u32_e32 v8, 16, v8
	s_waitcnt vmcnt(56)
	v_mov_b32_e32 v66, v174
	v_mov_b32_e32 v130, v175
	v_mov_b32_e32 v138, v176
	v_mov_b32_e32 v140, v177
	global_load_dword v174, v[210:211], off
	v_add_co_u32_e32 v210, vcc, 0x6000, v210
	v_addc_co_u32_e32 v211, vcc, 0, v211, vcc
	global_load_dword v175, v[210:211], off
	v_add_co_u32_e32 v210, vcc, 0x6000, v210
	v_addc_co_u32_e32 v211, vcc, 0, v211, vcc
	global_load_dword v176, v[210:211], off
	v_add_co_u32_e32 v210, vcc, 0x6000, v210
	v_addc_co_u32_e32 v211, vcc, 0, v211, vcc
	global_load_dword v177, v[210:211], off
	v_add_co_u32_e32 v210, vcc, 0x6000, v210
	v_addc_co_u32_e32 v211, vcc, 0, v211, vcc
	v_pk_fma_f32 v[4:5], v[66:67], v[142:143], v[4:5] op_sel_hi:[0,1,1]
	v_pk_fma_f32 v[68:69], v[66:67], v[144:145], v[68:69] op_sel_hi:[0,1,1]
	v_pk_fma_f32 v[70:71], v[66:67], v[146:147], v[70:71] op_sel_hi:[0,1,1]
	v_pk_fma_f32 v[72:73], v[66:67], v[148:149], v[72:73] op_sel_hi:[0,1,1]
	v_fmac_f32_e32 v23, v66, v134
	v_pk_fma_f32 v[4:5], v[130:131], v[98:99], v[4:5] op_sel_hi:[0,1,1]
	v_pk_fma_f32 v[68:69], v[130:131], v[106:107], v[68:69] op_sel_hi:[0,1,1]
	v_pk_fma_f32 v[70:71], v[130:131], v[114:115], v[70:71] op_sel_hi:[0,1,1]
	v_pk_fma_f32 v[72:73], v[130:131], v[122:123], v[72:73] op_sel_hi:[0,1,1]
	v_fmac_f32_e32 v23, v130, v135
	v_pk_fma_f32 v[4:5], v[138:139], v[102:103], v[4:5] op_sel_hi:[0,1,1]
	v_pk_fma_f32 v[68:69], v[138:139], v[110:111], v[68:69] op_sel_hi:[0,1,1]
	v_pk_fma_f32 v[70:71], v[138:139], v[118:119], v[70:71] op_sel_hi:[0,1,1]
	v_pk_fma_f32 v[72:73], v[138:139], v[126:127], v[72:73] op_sel_hi:[0,1,1]
	v_fmac_f32_e32 v23, v138, v136
	v_pk_fma_f32 v[4:5], v[140:141], v[100:101], v[4:5] op_sel_hi:[0,1,1]
	v_pk_fma_f32 v[68:69], v[140:141], v[108:109], v[68:69] op_sel_hi:[0,1,1]
	v_pk_fma_f32 v[70:71], v[140:141], v[116:117], v[70:71] op_sel_hi:[0,1,1]
	v_pk_fma_f32 v[72:73], v[140:141], v[124:125], v[72:73] op_sel_hi:[0,1,1]
	v_fmac_f32_e32 v23, v140, v137
	ds_read_b128 v[98:101], v8 offset:4096
	ds_read_b128 v[102:105], v8 offset:8192
	ds_read_b128 v[106:109], v8 offset:12288
	ds_read_b128 v[110:113], v8 offset:16384
	ds_read_b128 v[114:117], v8 offset:20480
	ds_read_b128 v[118:121], v8 offset:24576
	ds_read_b128 v[122:125], v8 offset:28672
	ds_read_b128 v[126:129], v8
	ds_read_b128 v[134:137], v8 offset:32768
	s_waitcnt lgkmcnt(0)
	v_mov_b32_e32 v143, v98
	v_mov_b32_e32 v144, v102
	v_mov_b32_e32 v145, v106
	v_mov_b32_e32 v142, v126
	v_mov_b32_e32 v146, v110
	v_mov_b32_e32 v147, v114
	v_mov_b32_e32 v148, v118
	v_mov_b32_e32 v149, v122
	v_mov_b32_e32 v98, v127
	v_mov_b32_e32 v106, v103
	v_mov_b32_e32 v114, v111
	v_mov_b32_e32 v122, v119
	v_mov_b32_e32 v102, v128
	v_mov_b32_e32 v103, v100
	v_mov_b32_e32 v110, v104
	v_mov_b32_e32 v111, v108
	v_mov_b32_e32 v118, v112
	v_mov_b32_e32 v119, v116
	v_mov_b32_e32 v126, v120
	v_mov_b32_e32 v127, v124
	v_mov_b32_e32 v100, v129
	v_mov_b32_e32 v108, v105
	v_mov_b32_e32 v116, v113
	v_mov_b32_e32 v124, v121
	v_add_u32_e32 v8, 16, v8
	s_waitcnt vmcnt(56)
	v_mov_b32_e32 v66, v178
	v_mov_b32_e32 v130, v179
	v_mov_b32_e32 v138, v180
	v_mov_b32_e32 v140, v181
	global_load_dword v178, v[210:211], off
	v_add_co_u32_e32 v210, vcc, 0x6000, v210
	v_addc_co_u32_e32 v211, vcc, 0, v211, vcc
	global_load_dword v179, v[210:211], off
	v_add_co_u32_e32 v210, vcc, 0x6000, v210
	v_addc_co_u32_e32 v211, vcc, 0, v211, vcc
	global_load_dword v180, v[210:211], off
	v_add_co_u32_e32 v210, vcc, 0x6000, v210
	v_addc_co_u32_e32 v211, vcc, 0, v211, vcc
	global_load_dword v181, v[210:211], off
	v_add_co_u32_e32 v210, vcc, 0x6000, v210
	v_addc_co_u32_e32 v211, vcc, 0, v211, vcc
	v_pk_fma_f32 v[4:5], v[66:67], v[142:143], v[4:5] op_sel_hi:[0,1,1]
	v_pk_fma_f32 v[68:69], v[66:67], v[144:145], v[68:69] op_sel_hi:[0,1,1]
	v_pk_fma_f32 v[70:71], v[66:67], v[146:147], v[70:71] op_sel_hi:[0,1,1]
	v_pk_fma_f32 v[72:73], v[66:67], v[148:149], v[72:73] op_sel_hi:[0,1,1]
	v_fmac_f32_e32 v23, v66, v134
	v_pk_fma_f32 v[4:5], v[130:131], v[98:99], v[4:5] op_sel_hi:[0,1,1]
	v_pk_fma_f32 v[68:69], v[130:131], v[106:107], v[68:69] op_sel_hi:[0,1,1]
	v_pk_fma_f32 v[70:71], v[130:131], v[114:115], v[70:71] op_sel_hi:[0,1,1]
	v_pk_fma_f32 v[72:73], v[130:131], v[122:123], v[72:73] op_sel_hi:[0,1,1]
	v_fmac_f32_e32 v23, v130, v135
	v_pk_fma_f32 v[4:5], v[138:139], v[102:103], v[4:5] op_sel_hi:[0,1,1]
	v_pk_fma_f32 v[68:69], v[138:139], v[110:111], v[68:69] op_sel_hi:[0,1,1]
	v_pk_fma_f32 v[70:71], v[138:139], v[118:119], v[70:71] op_sel_hi:[0,1,1]
	v_pk_fma_f32 v[72:73], v[138:139], v[126:127], v[72:73] op_sel_hi:[0,1,1]
	v_fmac_f32_e32 v23, v138, v136
	v_pk_fma_f32 v[4:5], v[140:141], v[100:101], v[4:5] op_sel_hi:[0,1,1]
	v_pk_fma_f32 v[68:69], v[140:141], v[108:109], v[68:69] op_sel_hi:[0,1,1]
	v_pk_fma_f32 v[70:71], v[140:141], v[116:117], v[70:71] op_sel_hi:[0,1,1]
	v_pk_fma_f32 v[72:73], v[140:141], v[124:125], v[72:73] op_sel_hi:[0,1,1]
	v_fmac_f32_e32 v23, v140, v137
	ds_read_b128 v[98:101], v8 offset:4096
	ds_read_b128 v[102:105], v8 offset:8192
	ds_read_b128 v[106:109], v8 offset:12288
	ds_read_b128 v[110:113], v8 offset:16384
	ds_read_b128 v[114:117], v8 offset:20480
	ds_read_b128 v[118:121], v8 offset:24576
	ds_read_b128 v[122:125], v8 offset:28672
	ds_read_b128 v[126:129], v8
	ds_read_b128 v[134:137], v8 offset:32768
	s_waitcnt lgkmcnt(0)
	v_mov_b32_e32 v143, v98
	v_mov_b32_e32 v144, v102
	v_mov_b32_e32 v145, v106
	v_mov_b32_e32 v142, v126
	v_mov_b32_e32 v146, v110
	v_mov_b32_e32 v147, v114
	v_mov_b32_e32 v148, v118
	v_mov_b32_e32 v149, v122
	v_mov_b32_e32 v98, v127
	v_mov_b32_e32 v106, v103
	v_mov_b32_e32 v114, v111
	v_mov_b32_e32 v122, v119
	v_mov_b32_e32 v102, v128
	v_mov_b32_e32 v103, v100
	v_mov_b32_e32 v110, v104
	v_mov_b32_e32 v111, v108
	v_mov_b32_e32 v118, v112
	v_mov_b32_e32 v119, v116
	v_mov_b32_e32 v126, v120
	v_mov_b32_e32 v127, v124
	v_mov_b32_e32 v100, v129
	v_mov_b32_e32 v108, v105
	v_mov_b32_e32 v116, v113
	v_mov_b32_e32 v124, v121
	v_add_u32_e32 v8, 16, v8
	s_waitcnt vmcnt(56)
	v_mov_b32_e32 v66, v182
	v_mov_b32_e32 v130, v183
	v_mov_b32_e32 v138, v184
	v_mov_b32_e32 v140, v185
	global_load_dword v182, v[210:211], off
	v_add_co_u32_e32 v210, vcc, 0x6000, v210
	v_addc_co_u32_e32 v211, vcc, 0, v211, vcc
	global_load_dword v183, v[210:211], off
	v_add_co_u32_e32 v210, vcc, 0x6000, v210
	v_addc_co_u32_e32 v211, vcc, 0, v211, vcc
	global_load_dword v184, v[210:211], off
	v_add_co_u32_e32 v210, vcc, 0x6000, v210
	v_addc_co_u32_e32 v211, vcc, 0, v211, vcc
	global_load_dword v185, v[210:211], off
	v_add_co_u32_e32 v210, vcc, 0x6000, v210
	v_addc_co_u32_e32 v211, vcc, 0, v211, vcc
	v_pk_fma_f32 v[4:5], v[66:67], v[142:143], v[4:5] op_sel_hi:[0,1,1]
	v_pk_fma_f32 v[68:69], v[66:67], v[144:145], v[68:69] op_sel_hi:[0,1,1]
	v_pk_fma_f32 v[70:71], v[66:67], v[146:147], v[70:71] op_sel_hi:[0,1,1]
	v_pk_fma_f32 v[72:73], v[66:67], v[148:149], v[72:73] op_sel_hi:[0,1,1]
	v_fmac_f32_e32 v23, v66, v134
	v_pk_fma_f32 v[4:5], v[130:131], v[98:99], v[4:5] op_sel_hi:[0,1,1]
	v_pk_fma_f32 v[68:69], v[130:131], v[106:107], v[68:69] op_sel_hi:[0,1,1]
	v_pk_fma_f32 v[70:71], v[130:131], v[114:115], v[70:71] op_sel_hi:[0,1,1]
	v_pk_fma_f32 v[72:73], v[130:131], v[122:123], v[72:73] op_sel_hi:[0,1,1]
	v_fmac_f32_e32 v23, v130, v135
	v_pk_fma_f32 v[4:5], v[138:139], v[102:103], v[4:5] op_sel_hi:[0,1,1]
	v_pk_fma_f32 v[68:69], v[138:139], v[110:111], v[68:69] op_sel_hi:[0,1,1]
	v_pk_fma_f32 v[70:71], v[138:139], v[118:119], v[70:71] op_sel_hi:[0,1,1]
	v_pk_fma_f32 v[72:73], v[138:139], v[126:127], v[72:73] op_sel_hi:[0,1,1]
	v_fmac_f32_e32 v23, v138, v136
	v_pk_fma_f32 v[4:5], v[140:141], v[100:101], v[4:5] op_sel_hi:[0,1,1]
	v_pk_fma_f32 v[68:69], v[140:141], v[108:109], v[68:69] op_sel_hi:[0,1,1]
	v_pk_fma_f32 v[70:71], v[140:141], v[116:117], v[70:71] op_sel_hi:[0,1,1]
	v_pk_fma_f32 v[72:73], v[140:141], v[124:125], v[72:73] op_sel_hi:[0,1,1]
	v_fmac_f32_e32 v23, v140, v137
	ds_read_b128 v[98:101], v8 offset:4096
	ds_read_b128 v[102:105], v8 offset:8192
	ds_read_b128 v[106:109], v8 offset:12288
	ds_read_b128 v[110:113], v8 offset:16384
	ds_read_b128 v[114:117], v8 offset:20480
	ds_read_b128 v[118:121], v8 offset:24576
	ds_read_b128 v[122:125], v8 offset:28672
	ds_read_b128 v[126:129], v8
	ds_read_b128 v[134:137], v8 offset:32768
	s_waitcnt lgkmcnt(0)
	v_mov_b32_e32 v143, v98
	v_mov_b32_e32 v144, v102
	v_mov_b32_e32 v145, v106
	v_mov_b32_e32 v142, v126
	v_mov_b32_e32 v146, v110
	v_mov_b32_e32 v147, v114
	v_mov_b32_e32 v148, v118
	v_mov_b32_e32 v149, v122
	v_mov_b32_e32 v98, v127
	v_mov_b32_e32 v106, v103
	v_mov_b32_e32 v114, v111
	v_mov_b32_e32 v122, v119
	v_mov_b32_e32 v102, v128
	v_mov_b32_e32 v103, v100
	v_mov_b32_e32 v110, v104
	v_mov_b32_e32 v111, v108
	v_mov_b32_e32 v118, v112
	v_mov_b32_e32 v119, v116
	v_mov_b32_e32 v126, v120
	v_mov_b32_e32 v127, v124
	v_mov_b32_e32 v100, v129
	v_mov_b32_e32 v108, v105
	v_mov_b32_e32 v116, v113
	v_mov_b32_e32 v124, v121
	v_add_u32_e32 v8, 16, v8
	s_waitcnt vmcnt(56)
	v_mov_b32_e32 v66, v186
	v_mov_b32_e32 v130, v187
	v_mov_b32_e32 v138, v188
	v_mov_b32_e32 v140, v189
	global_load_dword v186, v[210:211], off
	v_add_co_u32_e32 v210, vcc, 0x6000, v210
	v_addc_co_u32_e32 v211, vcc, 0, v211, vcc
	global_load_dword v187, v[210:211], off
	v_add_co_u32_e32 v210, vcc, 0x6000, v210
	v_addc_co_u32_e32 v211, vcc, 0, v211, vcc
	global_load_dword v188, v[210:211], off
	v_add_co_u32_e32 v210, vcc, 0x6000, v210
	v_addc_co_u32_e32 v211, vcc, 0, v211, vcc
	global_load_dword v189, v[210:211], off
	v_add_co_u32_e32 v210, vcc, 0x6000, v210
	v_addc_co_u32_e32 v211, vcc, 0, v211, vcc
	v_pk_fma_f32 v[4:5], v[66:67], v[142:143], v[4:5] op_sel_hi:[0,1,1]
	v_pk_fma_f32 v[68:69], v[66:67], v[144:145], v[68:69] op_sel_hi:[0,1,1]
	v_pk_fma_f32 v[70:71], v[66:67], v[146:147], v[70:71] op_sel_hi:[0,1,1]
	v_pk_fma_f32 v[72:73], v[66:67], v[148:149], v[72:73] op_sel_hi:[0,1,1]
	v_fmac_f32_e32 v23, v66, v134
	v_pk_fma_f32 v[4:5], v[130:131], v[98:99], v[4:5] op_sel_hi:[0,1,1]
	v_pk_fma_f32 v[68:69], v[130:131], v[106:107], v[68:69] op_sel_hi:[0,1,1]
	v_pk_fma_f32 v[70:71], v[130:131], v[114:115], v[70:71] op_sel_hi:[0,1,1]
	v_pk_fma_f32 v[72:73], v[130:131], v[122:123], v[72:73] op_sel_hi:[0,1,1]
	v_fmac_f32_e32 v23, v130, v135
	v_pk_fma_f32 v[4:5], v[138:139], v[102:103], v[4:5] op_sel_hi:[0,1,1]
	v_pk_fma_f32 v[68:69], v[138:139], v[110:111], v[68:69] op_sel_hi:[0,1,1]
	v_pk_fma_f32 v[70:71], v[138:139], v[118:119], v[70:71] op_sel_hi:[0,1,1]
	v_pk_fma_f32 v[72:73], v[138:139], v[126:127], v[72:73] op_sel_hi:[0,1,1]
	v_fmac_f32_e32 v23, v138, v136
	v_pk_fma_f32 v[4:5], v[140:141], v[100:101], v[4:5] op_sel_hi:[0,1,1]
	v_pk_fma_f32 v[68:69], v[140:141], v[108:109], v[68:69] op_sel_hi:[0,1,1]
	v_pk_fma_f32 v[70:71], v[140:141], v[116:117], v[70:71] op_sel_hi:[0,1,1]
	v_pk_fma_f32 v[72:73], v[140:141], v[124:125], v[72:73] op_sel_hi:[0,1,1]
	v_fmac_f32_e32 v23, v140, v137
	ds_read_b128 v[98:101], v8 offset:4096
	ds_read_b128 v[102:105], v8 offset:8192
	ds_read_b128 v[106:109], v8 offset:12288
	ds_read_b128 v[110:113], v8 offset:16384
	ds_read_b128 v[114:117], v8 offset:20480
	ds_read_b128 v[118:121], v8 offset:24576
	ds_read_b128 v[122:125], v8 offset:28672
	ds_read_b128 v[126:129], v8
	ds_read_b128 v[134:137], v8 offset:32768
	s_waitcnt lgkmcnt(0)
	v_mov_b32_e32 v143, v98
	v_mov_b32_e32 v144, v102
	v_mov_b32_e32 v145, v106
	v_mov_b32_e32 v142, v126
	v_mov_b32_e32 v146, v110
	v_mov_b32_e32 v147, v114
	v_mov_b32_e32 v148, v118
	v_mov_b32_e32 v149, v122
	v_mov_b32_e32 v98, v127
	v_mov_b32_e32 v106, v103
	v_mov_b32_e32 v114, v111
	v_mov_b32_e32 v122, v119
	v_mov_b32_e32 v102, v128
	v_mov_b32_e32 v103, v100
	v_mov_b32_e32 v110, v104
	v_mov_b32_e32 v111, v108
	v_mov_b32_e32 v118, v112
	v_mov_b32_e32 v119, v116
	v_mov_b32_e32 v126, v120
	v_mov_b32_e32 v127, v124
	v_mov_b32_e32 v100, v129
	v_mov_b32_e32 v108, v105
	v_mov_b32_e32 v116, v113
	v_mov_b32_e32 v124, v121
	v_add_u32_e32 v8, 16, v8
	s_waitcnt vmcnt(56)
	v_mov_b32_e32 v66, v190
	v_mov_b32_e32 v130, v191
	v_mov_b32_e32 v138, v192
	v_mov_b32_e32 v140, v193
	global_load_dword v190, v[210:211], off
	v_add_co_u32_e32 v210, vcc, 0x6000, v210
	v_addc_co_u32_e32 v211, vcc, 0, v211, vcc
	global_load_dword v191, v[210:211], off
	v_add_co_u32_e32 v210, vcc, 0x6000, v210
	v_addc_co_u32_e32 v211, vcc, 0, v211, vcc
	global_load_dword v192, v[210:211], off
	v_add_co_u32_e32 v210, vcc, 0x6000, v210
	v_addc_co_u32_e32 v211, vcc, 0, v211, vcc
	global_load_dword v193, v[210:211], off
	v_add_co_u32_e32 v210, vcc, 0x6000, v210
	v_addc_co_u32_e32 v211, vcc, 0, v211, vcc
	v_pk_fma_f32 v[4:5], v[66:67], v[142:143], v[4:5] op_sel_hi:[0,1,1]
	v_pk_fma_f32 v[68:69], v[66:67], v[144:145], v[68:69] op_sel_hi:[0,1,1]
	v_pk_fma_f32 v[70:71], v[66:67], v[146:147], v[70:71] op_sel_hi:[0,1,1]
	v_pk_fma_f32 v[72:73], v[66:67], v[148:149], v[72:73] op_sel_hi:[0,1,1]
	v_fmac_f32_e32 v23, v66, v134
	v_pk_fma_f32 v[4:5], v[130:131], v[98:99], v[4:5] op_sel_hi:[0,1,1]
	v_pk_fma_f32 v[68:69], v[130:131], v[106:107], v[68:69] op_sel_hi:[0,1,1]
	v_pk_fma_f32 v[70:71], v[130:131], v[114:115], v[70:71] op_sel_hi:[0,1,1]
	v_pk_fma_f32 v[72:73], v[130:131], v[122:123], v[72:73] op_sel_hi:[0,1,1]
	v_fmac_f32_e32 v23, v130, v135
	v_pk_fma_f32 v[4:5], v[138:139], v[102:103], v[4:5] op_sel_hi:[0,1,1]
	v_pk_fma_f32 v[68:69], v[138:139], v[110:111], v[68:69] op_sel_hi:[0,1,1]
	v_pk_fma_f32 v[70:71], v[138:139], v[118:119], v[70:71] op_sel_hi:[0,1,1]
	v_pk_fma_f32 v[72:73], v[138:139], v[126:127], v[72:73] op_sel_hi:[0,1,1]
	v_fmac_f32_e32 v23, v138, v136
	v_pk_fma_f32 v[4:5], v[140:141], v[100:101], v[4:5] op_sel_hi:[0,1,1]
	v_pk_fma_f32 v[68:69], v[140:141], v[108:109], v[68:69] op_sel_hi:[0,1,1]
	v_pk_fma_f32 v[70:71], v[140:141], v[116:117], v[70:71] op_sel_hi:[0,1,1]
	v_pk_fma_f32 v[72:73], v[140:141], v[124:125], v[72:73] op_sel_hi:[0,1,1]
	v_fmac_f32_e32 v23, v140, v137
	ds_read_b128 v[98:101], v8 offset:4096
	ds_read_b128 v[102:105], v8 offset:8192
	ds_read_b128 v[106:109], v8 offset:12288
	ds_read_b128 v[110:113], v8 offset:16384
	ds_read_b128 v[114:117], v8 offset:20480
	ds_read_b128 v[118:121], v8 offset:24576
	ds_read_b128 v[122:125], v8 offset:28672
	ds_read_b128 v[126:129], v8
	ds_read_b128 v[134:137], v8 offset:32768
	s_waitcnt lgkmcnt(0)
	v_mov_b32_e32 v143, v98
	v_mov_b32_e32 v144, v102
	v_mov_b32_e32 v145, v106
	v_mov_b32_e32 v142, v126
	v_mov_b32_e32 v146, v110
	v_mov_b32_e32 v147, v114
	v_mov_b32_e32 v148, v118
	v_mov_b32_e32 v149, v122
	v_mov_b32_e32 v98, v127
	v_mov_b32_e32 v106, v103
	v_mov_b32_e32 v114, v111
	v_mov_b32_e32 v122, v119
	v_mov_b32_e32 v102, v128
	v_mov_b32_e32 v103, v100
	v_mov_b32_e32 v110, v104
	v_mov_b32_e32 v111, v108
	v_mov_b32_e32 v118, v112
	v_mov_b32_e32 v119, v116
	v_mov_b32_e32 v126, v120
	v_mov_b32_e32 v127, v124
	v_mov_b32_e32 v100, v129
	v_mov_b32_e32 v108, v105
	v_mov_b32_e32 v116, v113
	v_mov_b32_e32 v124, v121
	v_add_u32_e32 v8, 16, v8
	s_waitcnt vmcnt(56)
	v_mov_b32_e32 v66, v194
	v_mov_b32_e32 v130, v195
	v_mov_b32_e32 v138, v196
	v_mov_b32_e32 v140, v197
	global_load_dword v194, v[210:211], off
	v_add_co_u32_e32 v210, vcc, 0x6000, v210
	v_addc_co_u32_e32 v211, vcc, 0, v211, vcc
	global_load_dword v195, v[210:211], off
	v_add_co_u32_e32 v210, vcc, 0x6000, v210
	v_addc_co_u32_e32 v211, vcc, 0, v211, vcc
	global_load_dword v196, v[210:211], off
	v_add_co_u32_e32 v210, vcc, 0x6000, v210
	v_addc_co_u32_e32 v211, vcc, 0, v211, vcc
	global_load_dword v197, v[210:211], off
	v_add_co_u32_e32 v210, vcc, 0x6000, v210
	v_addc_co_u32_e32 v211, vcc, 0, v211, vcc
	v_pk_fma_f32 v[4:5], v[66:67], v[142:143], v[4:5] op_sel_hi:[0,1,1]
	v_pk_fma_f32 v[68:69], v[66:67], v[144:145], v[68:69] op_sel_hi:[0,1,1]
	v_pk_fma_f32 v[70:71], v[66:67], v[146:147], v[70:71] op_sel_hi:[0,1,1]
	v_pk_fma_f32 v[72:73], v[66:67], v[148:149], v[72:73] op_sel_hi:[0,1,1]
	v_fmac_f32_e32 v23, v66, v134
	v_pk_fma_f32 v[4:5], v[130:131], v[98:99], v[4:5] op_sel_hi:[0,1,1]
	v_pk_fma_f32 v[68:69], v[130:131], v[106:107], v[68:69] op_sel_hi:[0,1,1]
	v_pk_fma_f32 v[70:71], v[130:131], v[114:115], v[70:71] op_sel_hi:[0,1,1]
	v_pk_fma_f32 v[72:73], v[130:131], v[122:123], v[72:73] op_sel_hi:[0,1,1]
	v_fmac_f32_e32 v23, v130, v135
	v_pk_fma_f32 v[4:5], v[138:139], v[102:103], v[4:5] op_sel_hi:[0,1,1]
	v_pk_fma_f32 v[68:69], v[138:139], v[110:111], v[68:69] op_sel_hi:[0,1,1]
	v_pk_fma_f32 v[70:71], v[138:139], v[118:119], v[70:71] op_sel_hi:[0,1,1]
	v_pk_fma_f32 v[72:73], v[138:139], v[126:127], v[72:73] op_sel_hi:[0,1,1]
	v_fmac_f32_e32 v23, v138, v136
	v_pk_fma_f32 v[4:5], v[140:141], v[100:101], v[4:5] op_sel_hi:[0,1,1]
	v_pk_fma_f32 v[68:69], v[140:141], v[108:109], v[68:69] op_sel_hi:[0,1,1]
	v_pk_fma_f32 v[70:71], v[140:141], v[116:117], v[70:71] op_sel_hi:[0,1,1]
	v_pk_fma_f32 v[72:73], v[140:141], v[124:125], v[72:73] op_sel_hi:[0,1,1]
	v_fmac_f32_e32 v23, v140, v137
	ds_read_b128 v[98:101], v8 offset:4096
	ds_read_b128 v[102:105], v8 offset:8192
	ds_read_b128 v[106:109], v8 offset:12288
	ds_read_b128 v[110:113], v8 offset:16384
	ds_read_b128 v[114:117], v8 offset:20480
	ds_read_b128 v[118:121], v8 offset:24576
	ds_read_b128 v[122:125], v8 offset:28672
	ds_read_b128 v[126:129], v8
	ds_read_b128 v[134:137], v8 offset:32768
	s_waitcnt lgkmcnt(0)
	v_mov_b32_e32 v143, v98
	v_mov_b32_e32 v144, v102
	v_mov_b32_e32 v145, v106
	v_mov_b32_e32 v142, v126
	v_mov_b32_e32 v146, v110
	v_mov_b32_e32 v147, v114
	v_mov_b32_e32 v148, v118
	v_mov_b32_e32 v149, v122
	v_mov_b32_e32 v98, v127
	v_mov_b32_e32 v106, v103
	v_mov_b32_e32 v114, v111
	v_mov_b32_e32 v122, v119
	v_mov_b32_e32 v102, v128
	v_mov_b32_e32 v103, v100
	v_mov_b32_e32 v110, v104
	v_mov_b32_e32 v111, v108
	v_mov_b32_e32 v118, v112
	v_mov_b32_e32 v119, v116
	v_mov_b32_e32 v126, v120
	v_mov_b32_e32 v127, v124
	v_mov_b32_e32 v100, v129
	v_mov_b32_e32 v108, v105
	v_mov_b32_e32 v116, v113
	v_mov_b32_e32 v124, v121
	v_add_u32_e32 v8, 16, v8
	s_waitcnt vmcnt(56)
	v_mov_b32_e32 v66, v198
	v_mov_b32_e32 v130, v199
	v_mov_b32_e32 v138, v200
	v_mov_b32_e32 v140, v201
	global_load_dword v198, v[210:211], off
	v_add_co_u32_e32 v210, vcc, 0x6000, v210
	v_addc_co_u32_e32 v211, vcc, 0, v211, vcc
	global_load_dword v199, v[210:211], off
	v_add_co_u32_e32 v210, vcc, 0x6000, v210
	v_addc_co_u32_e32 v211, vcc, 0, v211, vcc
	global_load_dword v200, v[210:211], off
	v_add_co_u32_e32 v210, vcc, 0x6000, v210
	v_addc_co_u32_e32 v211, vcc, 0, v211, vcc
	global_load_dword v201, v[210:211], off
	v_add_co_u32_e32 v210, vcc, 0x6000, v210
	v_addc_co_u32_e32 v211, vcc, 0, v211, vcc
	v_pk_fma_f32 v[4:5], v[66:67], v[142:143], v[4:5] op_sel_hi:[0,1,1]
	v_pk_fma_f32 v[68:69], v[66:67], v[144:145], v[68:69] op_sel_hi:[0,1,1]
	v_pk_fma_f32 v[70:71], v[66:67], v[146:147], v[70:71] op_sel_hi:[0,1,1]
	v_pk_fma_f32 v[72:73], v[66:67], v[148:149], v[72:73] op_sel_hi:[0,1,1]
	v_fmac_f32_e32 v23, v66, v134
	v_pk_fma_f32 v[4:5], v[130:131], v[98:99], v[4:5] op_sel_hi:[0,1,1]
	v_pk_fma_f32 v[68:69], v[130:131], v[106:107], v[68:69] op_sel_hi:[0,1,1]
	v_pk_fma_f32 v[70:71], v[130:131], v[114:115], v[70:71] op_sel_hi:[0,1,1]
	v_pk_fma_f32 v[72:73], v[130:131], v[122:123], v[72:73] op_sel_hi:[0,1,1]
	v_fmac_f32_e32 v23, v130, v135
	v_pk_fma_f32 v[4:5], v[138:139], v[102:103], v[4:5] op_sel_hi:[0,1,1]
	v_pk_fma_f32 v[68:69], v[138:139], v[110:111], v[68:69] op_sel_hi:[0,1,1]
	v_pk_fma_f32 v[70:71], v[138:139], v[118:119], v[70:71] op_sel_hi:[0,1,1]
	v_pk_fma_f32 v[72:73], v[138:139], v[126:127], v[72:73] op_sel_hi:[0,1,1]
	v_fmac_f32_e32 v23, v138, v136
	v_pk_fma_f32 v[4:5], v[140:141], v[100:101], v[4:5] op_sel_hi:[0,1,1]
	v_pk_fma_f32 v[68:69], v[140:141], v[108:109], v[68:69] op_sel_hi:[0,1,1]
	v_pk_fma_f32 v[70:71], v[140:141], v[116:117], v[70:71] op_sel_hi:[0,1,1]
	v_pk_fma_f32 v[72:73], v[140:141], v[124:125], v[72:73] op_sel_hi:[0,1,1]
	v_fmac_f32_e32 v23, v140, v137
	ds_read_b128 v[98:101], v8 offset:4096
	ds_read_b128 v[102:105], v8 offset:8192
	ds_read_b128 v[106:109], v8 offset:12288
	ds_read_b128 v[110:113], v8 offset:16384
	ds_read_b128 v[114:117], v8 offset:20480
	ds_read_b128 v[118:121], v8 offset:24576
	ds_read_b128 v[122:125], v8 offset:28672
	ds_read_b128 v[126:129], v8
	ds_read_b128 v[134:137], v8 offset:32768
	s_waitcnt lgkmcnt(0)
	v_mov_b32_e32 v143, v98
	v_mov_b32_e32 v144, v102
	v_mov_b32_e32 v145, v106
	v_mov_b32_e32 v142, v126
	v_mov_b32_e32 v146, v110
	v_mov_b32_e32 v147, v114
	v_mov_b32_e32 v148, v118
	v_mov_b32_e32 v149, v122
	v_mov_b32_e32 v98, v127
	v_mov_b32_e32 v106, v103
	v_mov_b32_e32 v114, v111
	v_mov_b32_e32 v122, v119
	v_mov_b32_e32 v102, v128
	v_mov_b32_e32 v103, v100
	v_mov_b32_e32 v110, v104
	v_mov_b32_e32 v111, v108
	v_mov_b32_e32 v118, v112
	v_mov_b32_e32 v119, v116
	v_mov_b32_e32 v126, v120
	v_mov_b32_e32 v127, v124
	v_mov_b32_e32 v100, v129
	v_mov_b32_e32 v108, v105
	v_mov_b32_e32 v116, v113
	v_mov_b32_e32 v124, v121
	v_add_u32_e32 v8, 16, v8
	s_waitcnt vmcnt(56)
	v_mov_b32_e32 v66, v202
	v_mov_b32_e32 v130, v203
	v_mov_b32_e32 v138, v204
	v_mov_b32_e32 v140, v205
	global_load_dword v202, v[210:211], off
	v_add_co_u32_e32 v210, vcc, 0x6000, v210
	v_addc_co_u32_e32 v211, vcc, 0, v211, vcc
	global_load_dword v203, v[210:211], off
	v_add_co_u32_e32 v210, vcc, 0x6000, v210
	v_addc_co_u32_e32 v211, vcc, 0, v211, vcc
	global_load_dword v204, v[210:211], off
	v_add_co_u32_e32 v210, vcc, 0x6000, v210
	v_addc_co_u32_e32 v211, vcc, 0, v211, vcc
	global_load_dword v205, v[210:211], off
	v_add_co_u32_e32 v210, vcc, 0x6000, v210
	v_addc_co_u32_e32 v211, vcc, 0, v211, vcc
	v_pk_fma_f32 v[4:5], v[66:67], v[142:143], v[4:5] op_sel_hi:[0,1,1]
	v_pk_fma_f32 v[68:69], v[66:67], v[144:145], v[68:69] op_sel_hi:[0,1,1]
	v_pk_fma_f32 v[70:71], v[66:67], v[146:147], v[70:71] op_sel_hi:[0,1,1]
	v_pk_fma_f32 v[72:73], v[66:67], v[148:149], v[72:73] op_sel_hi:[0,1,1]
	v_fmac_f32_e32 v23, v66, v134
	v_pk_fma_f32 v[4:5], v[130:131], v[98:99], v[4:5] op_sel_hi:[0,1,1]
	v_pk_fma_f32 v[68:69], v[130:131], v[106:107], v[68:69] op_sel_hi:[0,1,1]
	v_pk_fma_f32 v[70:71], v[130:131], v[114:115], v[70:71] op_sel_hi:[0,1,1]
	v_pk_fma_f32 v[72:73], v[130:131], v[122:123], v[72:73] op_sel_hi:[0,1,1]
	v_fmac_f32_e32 v23, v130, v135
	v_pk_fma_f32 v[4:5], v[138:139], v[102:103], v[4:5] op_sel_hi:[0,1,1]
	v_pk_fma_f32 v[68:69], v[138:139], v[110:111], v[68:69] op_sel_hi:[0,1,1]
	v_pk_fma_f32 v[70:71], v[138:139], v[118:119], v[70:71] op_sel_hi:[0,1,1]
	v_pk_fma_f32 v[72:73], v[138:139], v[126:127], v[72:73] op_sel_hi:[0,1,1]
	v_fmac_f32_e32 v23, v138, v136
	v_pk_fma_f32 v[4:5], v[140:141], v[100:101], v[4:5] op_sel_hi:[0,1,1]
	v_pk_fma_f32 v[68:69], v[140:141], v[108:109], v[68:69] op_sel_hi:[0,1,1]
	v_pk_fma_f32 v[70:71], v[140:141], v[116:117], v[70:71] op_sel_hi:[0,1,1]
	v_pk_fma_f32 v[72:73], v[140:141], v[124:125], v[72:73] op_sel_hi:[0,1,1]
	v_fmac_f32_e32 v23, v140, v137
	ds_read_b128 v[98:101], v8 offset:4096
	ds_read_b128 v[102:105], v8 offset:8192
	ds_read_b128 v[106:109], v8 offset:12288
	ds_read_b128 v[110:113], v8 offset:16384
	ds_read_b128 v[114:117], v8 offset:20480
	ds_read_b128 v[118:121], v8 offset:24576
	ds_read_b128 v[122:125], v8 offset:28672
	ds_read_b128 v[126:129], v8
	ds_read_b128 v[134:137], v8 offset:32768
	s_waitcnt lgkmcnt(0)
	v_mov_b32_e32 v143, v98
	v_mov_b32_e32 v144, v102
	v_mov_b32_e32 v145, v106
	v_mov_b32_e32 v142, v126
	v_mov_b32_e32 v146, v110
	v_mov_b32_e32 v147, v114
	v_mov_b32_e32 v148, v118
	v_mov_b32_e32 v149, v122
	v_mov_b32_e32 v98, v127
	v_mov_b32_e32 v106, v103
	v_mov_b32_e32 v114, v111
	v_mov_b32_e32 v122, v119
	v_mov_b32_e32 v102, v128
	v_mov_b32_e32 v103, v100
	v_mov_b32_e32 v110, v104
	v_mov_b32_e32 v111, v108
	v_mov_b32_e32 v118, v112
	v_mov_b32_e32 v119, v116
	v_mov_b32_e32 v126, v120
	v_mov_b32_e32 v127, v124
	v_mov_b32_e32 v100, v129
	v_mov_b32_e32 v108, v105
	v_mov_b32_e32 v116, v113
	v_mov_b32_e32 v124, v121
	v_add_u32_e32 v8, 16, v8
	s_waitcnt vmcnt(56)
	v_mov_b32_e32 v66, v206
	v_mov_b32_e32 v130, v207
	v_mov_b32_e32 v138, v208
	v_mov_b32_e32 v140, v209
	global_load_dword v206, v[210:211], off
	v_add_co_u32_e32 v210, vcc, 0x6000, v210
	v_addc_co_u32_e32 v211, vcc, 0, v211, vcc
	global_load_dword v207, v[210:211], off
	v_add_co_u32_e32 v210, vcc, 0x6000, v210
	v_addc_co_u32_e32 v211, vcc, 0, v211, vcc
	global_load_dword v208, v[210:211], off
	v_add_co_u32_e32 v210, vcc, 0x6000, v210
	v_addc_co_u32_e32 v211, vcc, 0, v211, vcc
	global_load_dword v209, v[210:211], off
	v_add_co_u32_e32 v210, vcc, 0x6000, v210
	v_addc_co_u32_e32 v211, vcc, 0, v211, vcc
	v_pk_fma_f32 v[4:5], v[66:67], v[142:143], v[4:5] op_sel_hi:[0,1,1]
	v_pk_fma_f32 v[68:69], v[66:67], v[144:145], v[68:69] op_sel_hi:[0,1,1]
	v_pk_fma_f32 v[70:71], v[66:67], v[146:147], v[70:71] op_sel_hi:[0,1,1]
	v_pk_fma_f32 v[72:73], v[66:67], v[148:149], v[72:73] op_sel_hi:[0,1,1]
	v_fmac_f32_e32 v23, v66, v134
	v_pk_fma_f32 v[4:5], v[130:131], v[98:99], v[4:5] op_sel_hi:[0,1,1]
	v_pk_fma_f32 v[68:69], v[130:131], v[106:107], v[68:69] op_sel_hi:[0,1,1]
	v_pk_fma_f32 v[70:71], v[130:131], v[114:115], v[70:71] op_sel_hi:[0,1,1]
	v_pk_fma_f32 v[72:73], v[130:131], v[122:123], v[72:73] op_sel_hi:[0,1,1]
	v_fmac_f32_e32 v23, v130, v135
	v_pk_fma_f32 v[4:5], v[138:139], v[102:103], v[4:5] op_sel_hi:[0,1,1]
	v_pk_fma_f32 v[68:69], v[138:139], v[110:111], v[68:69] op_sel_hi:[0,1,1]
	v_pk_fma_f32 v[70:71], v[138:139], v[118:119], v[70:71] op_sel_hi:[0,1,1]
	v_pk_fma_f32 v[72:73], v[138:139], v[126:127], v[72:73] op_sel_hi:[0,1,1]
	v_fmac_f32_e32 v23, v138, v136
	v_pk_fma_f32 v[4:5], v[140:141], v[100:101], v[4:5] op_sel_hi:[0,1,1]
	v_pk_fma_f32 v[68:69], v[140:141], v[108:109], v[68:69] op_sel_hi:[0,1,1]
	v_pk_fma_f32 v[70:71], v[140:141], v[116:117], v[70:71] op_sel_hi:[0,1,1]
	v_pk_fma_f32 v[72:73], v[140:141], v[124:125], v[72:73] op_sel_hi:[0,1,1]
	v_fmac_f32_e32 v23, v140, v137
	ds_read_b128 v[98:101], v8 offset:4096
	ds_read_b128 v[102:105], v8 offset:8192
	ds_read_b128 v[106:109], v8 offset:12288
	ds_read_b128 v[110:113], v8 offset:16384
	ds_read_b128 v[114:117], v8 offset:20480
	ds_read_b128 v[118:121], v8 offset:24576
	ds_read_b128 v[122:125], v8 offset:28672
	ds_read_b128 v[126:129], v8
	ds_read_b128 v[134:137], v8 offset:32768
	s_waitcnt lgkmcnt(0)
	v_mov_b32_e32 v143, v98
	v_mov_b32_e32 v144, v102
	v_mov_b32_e32 v145, v106
	v_mov_b32_e32 v142, v126
	v_mov_b32_e32 v146, v110
	v_mov_b32_e32 v147, v114
	v_mov_b32_e32 v148, v118
	v_mov_b32_e32 v149, v122
	v_mov_b32_e32 v98, v127
	v_mov_b32_e32 v106, v103
	v_mov_b32_e32 v114, v111
	v_mov_b32_e32 v122, v119
	v_mov_b32_e32 v102, v128
	v_mov_b32_e32 v103, v100
	v_mov_b32_e32 v110, v104
	v_mov_b32_e32 v111, v108
	v_mov_b32_e32 v118, v112
	v_mov_b32_e32 v119, v116
	v_mov_b32_e32 v126, v120
	v_mov_b32_e32 v127, v124
	v_mov_b32_e32 v100, v129
	v_mov_b32_e32 v108, v105
	v_mov_b32_e32 v116, v113
	v_mov_b32_e32 v124, v121
	v_add_u32_e32 v8, 16, v8
	s_waitcnt vmcnt(56)
	v_mov_b32_e32 v66, v150
	v_mov_b32_e32 v130, v151
	v_mov_b32_e32 v138, v152
	v_mov_b32_e32 v140, v153
	global_load_dword v150, v[210:211], off
	v_add_co_u32_e32 v210, vcc, 0x6000, v210
	v_addc_co_u32_e32 v211, vcc, 0, v211, vcc
	global_load_dword v151, v[210:211], off
	v_add_co_u32_e32 v210, vcc, 0x6000, v210
	v_addc_co_u32_e32 v211, vcc, 0, v211, vcc
	global_load_dword v152, v[210:211], off
	v_add_co_u32_e32 v210, vcc, 0x6000, v210
	v_addc_co_u32_e32 v211, vcc, 0, v211, vcc
	global_load_dword v153, v[210:211], off
	v_add_co_u32_e32 v210, vcc, 0x6000, v210
	v_addc_co_u32_e32 v211, vcc, 0, v211, vcc
	v_pk_fma_f32 v[4:5], v[66:67], v[142:143], v[4:5] op_sel_hi:[0,1,1]
	v_pk_fma_f32 v[68:69], v[66:67], v[144:145], v[68:69] op_sel_hi:[0,1,1]
	v_pk_fma_f32 v[70:71], v[66:67], v[146:147], v[70:71] op_sel_hi:[0,1,1]
	v_pk_fma_f32 v[72:73], v[66:67], v[148:149], v[72:73] op_sel_hi:[0,1,1]
	v_fmac_f32_e32 v23, v66, v134
	v_pk_fma_f32 v[4:5], v[130:131], v[98:99], v[4:5] op_sel_hi:[0,1,1]
	v_pk_fma_f32 v[68:69], v[130:131], v[106:107], v[68:69] op_sel_hi:[0,1,1]
	v_pk_fma_f32 v[70:71], v[130:131], v[114:115], v[70:71] op_sel_hi:[0,1,1]
	v_pk_fma_f32 v[72:73], v[130:131], v[122:123], v[72:73] op_sel_hi:[0,1,1]
	v_fmac_f32_e32 v23, v130, v135
	v_pk_fma_f32 v[4:5], v[138:139], v[102:103], v[4:5] op_sel_hi:[0,1,1]
	v_pk_fma_f32 v[68:69], v[138:139], v[110:111], v[68:69] op_sel_hi:[0,1,1]
	v_pk_fma_f32 v[70:71], v[138:139], v[118:119], v[70:71] op_sel_hi:[0,1,1]
	v_pk_fma_f32 v[72:73], v[138:139], v[126:127], v[72:73] op_sel_hi:[0,1,1]
	v_fmac_f32_e32 v23, v138, v136
	v_pk_fma_f32 v[4:5], v[140:141], v[100:101], v[4:5] op_sel_hi:[0,1,1]
	v_pk_fma_f32 v[68:69], v[140:141], v[108:109], v[68:69] op_sel_hi:[0,1,1]
	v_pk_fma_f32 v[70:71], v[140:141], v[116:117], v[70:71] op_sel_hi:[0,1,1]
	v_pk_fma_f32 v[72:73], v[140:141], v[124:125], v[72:73] op_sel_hi:[0,1,1]
	v_fmac_f32_e32 v23, v140, v137
	ds_read_b128 v[98:101], v8 offset:4096
	ds_read_b128 v[102:105], v8 offset:8192
	ds_read_b128 v[106:109], v8 offset:12288
	ds_read_b128 v[110:113], v8 offset:16384
	ds_read_b128 v[114:117], v8 offset:20480
	ds_read_b128 v[118:121], v8 offset:24576
	ds_read_b128 v[122:125], v8 offset:28672
	ds_read_b128 v[126:129], v8
	ds_read_b128 v[134:137], v8 offset:32768
	s_waitcnt lgkmcnt(0)
	v_mov_b32_e32 v143, v98
	v_mov_b32_e32 v144, v102
	v_mov_b32_e32 v145, v106
	v_mov_b32_e32 v142, v126
	v_mov_b32_e32 v146, v110
	v_mov_b32_e32 v147, v114
	v_mov_b32_e32 v148, v118
	v_mov_b32_e32 v149, v122
	v_mov_b32_e32 v98, v127
	v_mov_b32_e32 v106, v103
	v_mov_b32_e32 v114, v111
	v_mov_b32_e32 v122, v119
	v_mov_b32_e32 v102, v128
	v_mov_b32_e32 v103, v100
	v_mov_b32_e32 v110, v104
	v_mov_b32_e32 v111, v108
	v_mov_b32_e32 v118, v112
	v_mov_b32_e32 v119, v116
	v_mov_b32_e32 v126, v120
	v_mov_b32_e32 v127, v124
	v_mov_b32_e32 v100, v129
	v_mov_b32_e32 v108, v105
	v_mov_b32_e32 v116, v113
	v_mov_b32_e32 v124, v121
	v_add_u32_e32 v8, 16, v8
	s_waitcnt vmcnt(56)
	v_mov_b32_e32 v66, v154
	v_mov_b32_e32 v130, v155
	v_mov_b32_e32 v138, v156
	v_mov_b32_e32 v140, v157
	global_load_dword v154, v[210:211], off
	v_add_co_u32_e32 v210, vcc, 0x6000, v210
	v_addc_co_u32_e32 v211, vcc, 0, v211, vcc
	global_load_dword v155, v[210:211], off
	v_add_co_u32_e32 v210, vcc, 0x6000, v210
	v_addc_co_u32_e32 v211, vcc, 0, v211, vcc
	global_load_dword v156, v[210:211], off
	v_add_co_u32_e32 v210, vcc, 0x6000, v210
	v_addc_co_u32_e32 v211, vcc, 0, v211, vcc
	global_load_dword v157, v[210:211], off
	v_pk_fma_f32 v[4:5], v[66:67], v[142:143], v[4:5] op_sel_hi:[0,1,1]
	v_pk_fma_f32 v[68:69], v[66:67], v[144:145], v[68:69] op_sel_hi:[0,1,1]
	v_pk_fma_f32 v[70:71], v[66:67], v[146:147], v[70:71] op_sel_hi:[0,1,1]
	v_pk_fma_f32 v[72:73], v[66:67], v[148:149], v[72:73] op_sel_hi:[0,1,1]
	v_fmac_f32_e32 v23, v66, v134
	v_pk_fma_f32 v[4:5], v[130:131], v[98:99], v[4:5] op_sel_hi:[0,1,1]
	v_pk_fma_f32 v[68:69], v[130:131], v[106:107], v[68:69] op_sel_hi:[0,1,1]
	v_pk_fma_f32 v[70:71], v[130:131], v[114:115], v[70:71] op_sel_hi:[0,1,1]
	v_pk_fma_f32 v[72:73], v[130:131], v[122:123], v[72:73] op_sel_hi:[0,1,1]
	v_fmac_f32_e32 v23, v130, v135
	v_pk_fma_f32 v[4:5], v[138:139], v[102:103], v[4:5] op_sel_hi:[0,1,1]
	v_pk_fma_f32 v[68:69], v[138:139], v[110:111], v[68:69] op_sel_hi:[0,1,1]
	v_pk_fma_f32 v[70:71], v[138:139], v[118:119], v[70:71] op_sel_hi:[0,1,1]
	v_pk_fma_f32 v[72:73], v[138:139], v[126:127], v[72:73] op_sel_hi:[0,1,1]
	v_fmac_f32_e32 v23, v138, v136
	v_pk_fma_f32 v[4:5], v[140:141], v[100:101], v[4:5] op_sel_hi:[0,1,1]
	v_pk_fma_f32 v[68:69], v[140:141], v[108:109], v[68:69] op_sel_hi:[0,1,1]
	v_pk_fma_f32 v[70:71], v[140:141], v[116:117], v[70:71] op_sel_hi:[0,1,1]
	v_pk_fma_f32 v[72:73], v[140:141], v[124:125], v[72:73] op_sel_hi:[0,1,1]
	v_fmac_f32_e32 v23, v140, v137
	ds_read_b128 v[98:101], v8 offset:4096
	ds_read_b128 v[102:105], v8 offset:8192
	ds_read_b128 v[106:109], v8 offset:12288
	ds_read_b128 v[110:113], v8 offset:16384
	ds_read_b128 v[114:117], v8 offset:20480
	ds_read_b128 v[118:121], v8 offset:24576
	ds_read_b128 v[122:125], v8 offset:28672
	ds_read_b128 v[126:129], v8
	ds_read_b128 v[134:137], v8 offset:32768
	s_waitcnt lgkmcnt(0)
	v_mov_b32_e32 v143, v98
	v_mov_b32_e32 v144, v102
	v_mov_b32_e32 v145, v106
	v_mov_b32_e32 v142, v126
	v_mov_b32_e32 v146, v110
	v_mov_b32_e32 v147, v114
	v_mov_b32_e32 v148, v118
	v_mov_b32_e32 v149, v122
	v_mov_b32_e32 v98, v127
	v_mov_b32_e32 v106, v103
	v_mov_b32_e32 v114, v111
	v_mov_b32_e32 v122, v119
	v_mov_b32_e32 v102, v128
	v_mov_b32_e32 v103, v100
	v_mov_b32_e32 v110, v104
	v_mov_b32_e32 v111, v108
	v_mov_b32_e32 v118, v112
	v_mov_b32_e32 v119, v116
	v_mov_b32_e32 v126, v120
	v_mov_b32_e32 v127, v124
	v_mov_b32_e32 v100, v129
	v_mov_b32_e32 v108, v105
	v_mov_b32_e32 v116, v113
	v_mov_b32_e32 v124, v121
	v_add_u32_e32 v8, 16, v8
	s_waitcnt vmcnt(56)
	v_mov_b32_e32 v66, v158
	v_mov_b32_e32 v130, v159
	v_mov_b32_e32 v138, v160
	v_mov_b32_e32 v140, v161
	v_pk_fma_f32 v[4:5], v[66:67], v[142:143], v[4:5] op_sel_hi:[0,1,1]
	v_pk_fma_f32 v[68:69], v[66:67], v[144:145], v[68:69] op_sel_hi:[0,1,1]
	v_pk_fma_f32 v[70:71], v[66:67], v[146:147], v[70:71] op_sel_hi:[0,1,1]
	v_pk_fma_f32 v[72:73], v[66:67], v[148:149], v[72:73] op_sel_hi:[0,1,1]
	v_fmac_f32_e32 v23, v66, v134
	v_pk_fma_f32 v[4:5], v[130:131], v[98:99], v[4:5] op_sel_hi:[0,1,1]
	v_pk_fma_f32 v[68:69], v[130:131], v[106:107], v[68:69] op_sel_hi:[0,1,1]
	v_pk_fma_f32 v[70:71], v[130:131], v[114:115], v[70:71] op_sel_hi:[0,1,1]
	v_pk_fma_f32 v[72:73], v[130:131], v[122:123], v[72:73] op_sel_hi:[0,1,1]
	v_fmac_f32_e32 v23, v130, v135
	v_pk_fma_f32 v[4:5], v[138:139], v[102:103], v[4:5] op_sel_hi:[0,1,1]
	v_pk_fma_f32 v[68:69], v[138:139], v[110:111], v[68:69] op_sel_hi:[0,1,1]
	v_pk_fma_f32 v[70:71], v[138:139], v[118:119], v[70:71] op_sel_hi:[0,1,1]
	v_pk_fma_f32 v[72:73], v[138:139], v[126:127], v[72:73] op_sel_hi:[0,1,1]
	v_fmac_f32_e32 v23, v138, v136
	v_pk_fma_f32 v[4:5], v[140:141], v[100:101], v[4:5] op_sel_hi:[0,1,1]
	v_pk_fma_f32 v[68:69], v[140:141], v[108:109], v[68:69] op_sel_hi:[0,1,1]
	v_pk_fma_f32 v[70:71], v[140:141], v[116:117], v[70:71] op_sel_hi:[0,1,1]
	v_pk_fma_f32 v[72:73], v[140:141], v[124:125], v[72:73] op_sel_hi:[0,1,1]
	v_fmac_f32_e32 v23, v140, v137
	ds_read_b128 v[98:101], v8 offset:4096
	ds_read_b128 v[102:105], v8 offset:8192
	ds_read_b128 v[106:109], v8 offset:12288
	ds_read_b128 v[110:113], v8 offset:16384
	ds_read_b128 v[114:117], v8 offset:20480
	ds_read_b128 v[118:121], v8 offset:24576
	ds_read_b128 v[122:125], v8 offset:28672
	ds_read_b128 v[126:129], v8
	ds_read_b128 v[134:137], v8 offset:32768
	s_waitcnt lgkmcnt(0)
	v_mov_b32_e32 v143, v98
	v_mov_b32_e32 v144, v102
	v_mov_b32_e32 v145, v106
	v_mov_b32_e32 v142, v126
	v_mov_b32_e32 v146, v110
	v_mov_b32_e32 v147, v114
	v_mov_b32_e32 v148, v118
	v_mov_b32_e32 v149, v122
	v_mov_b32_e32 v98, v127
	v_mov_b32_e32 v106, v103
	v_mov_b32_e32 v114, v111
	v_mov_b32_e32 v122, v119
	v_mov_b32_e32 v102, v128
	v_mov_b32_e32 v103, v100
	v_mov_b32_e32 v110, v104
	v_mov_b32_e32 v111, v108
	v_mov_b32_e32 v118, v112
	v_mov_b32_e32 v119, v116
	v_mov_b32_e32 v126, v120
	v_mov_b32_e32 v127, v124
	v_mov_b32_e32 v100, v129
	v_mov_b32_e32 v108, v105
	v_mov_b32_e32 v116, v113
	v_mov_b32_e32 v124, v121
	v_add_u32_e32 v8, 16, v8
	s_waitcnt vmcnt(52)
	v_mov_b32_e32 v66, v162
	v_mov_b32_e32 v130, v163
	v_mov_b32_e32 v138, v164
	v_mov_b32_e32 v140, v165
	v_pk_fma_f32 v[4:5], v[66:67], v[142:143], v[4:5] op_sel_hi:[0,1,1]
	v_pk_fma_f32 v[68:69], v[66:67], v[144:145], v[68:69] op_sel_hi:[0,1,1]
	v_pk_fma_f32 v[70:71], v[66:67], v[146:147], v[70:71] op_sel_hi:[0,1,1]
	v_pk_fma_f32 v[72:73], v[66:67], v[148:149], v[72:73] op_sel_hi:[0,1,1]
	v_fmac_f32_e32 v23, v66, v134
	v_pk_fma_f32 v[4:5], v[130:131], v[98:99], v[4:5] op_sel_hi:[0,1,1]
	v_pk_fma_f32 v[68:69], v[130:131], v[106:107], v[68:69] op_sel_hi:[0,1,1]
	v_pk_fma_f32 v[70:71], v[130:131], v[114:115], v[70:71] op_sel_hi:[0,1,1]
	v_pk_fma_f32 v[72:73], v[130:131], v[122:123], v[72:73] op_sel_hi:[0,1,1]
	v_fmac_f32_e32 v23, v130, v135
	v_pk_fma_f32 v[4:5], v[138:139], v[102:103], v[4:5] op_sel_hi:[0,1,1]
	v_pk_fma_f32 v[68:69], v[138:139], v[110:111], v[68:69] op_sel_hi:[0,1,1]
	v_pk_fma_f32 v[70:71], v[138:139], v[118:119], v[70:71] op_sel_hi:[0,1,1]
	v_pk_fma_f32 v[72:73], v[138:139], v[126:127], v[72:73] op_sel_hi:[0,1,1]
	v_fmac_f32_e32 v23, v138, v136
	v_pk_fma_f32 v[4:5], v[140:141], v[100:101], v[4:5] op_sel_hi:[0,1,1]
	v_pk_fma_f32 v[68:69], v[140:141], v[108:109], v[68:69] op_sel_hi:[0,1,1]
	v_pk_fma_f32 v[70:71], v[140:141], v[116:117], v[70:71] op_sel_hi:[0,1,1]
	v_pk_fma_f32 v[72:73], v[140:141], v[124:125], v[72:73] op_sel_hi:[0,1,1]
	v_fmac_f32_e32 v23, v140, v137
	ds_read_b128 v[98:101], v8 offset:4096
	ds_read_b128 v[102:105], v8 offset:8192
	ds_read_b128 v[106:109], v8 offset:12288
	ds_read_b128 v[110:113], v8 offset:16384
	ds_read_b128 v[114:117], v8 offset:20480
	ds_read_b128 v[118:121], v8 offset:24576
	ds_read_b128 v[122:125], v8 offset:28672
	ds_read_b128 v[126:129], v8
	ds_read_b128 v[134:137], v8 offset:32768
	s_waitcnt lgkmcnt(0)
	v_mov_b32_e32 v143, v98
	v_mov_b32_e32 v144, v102
	v_mov_b32_e32 v145, v106
	v_mov_b32_e32 v142, v126
	v_mov_b32_e32 v146, v110
	v_mov_b32_e32 v147, v114
	v_mov_b32_e32 v148, v118
	v_mov_b32_e32 v149, v122
	v_mov_b32_e32 v98, v127
	v_mov_b32_e32 v106, v103
	v_mov_b32_e32 v114, v111
	v_mov_b32_e32 v122, v119
	v_mov_b32_e32 v102, v128
	v_mov_b32_e32 v103, v100
	v_mov_b32_e32 v110, v104
	v_mov_b32_e32 v111, v108
	v_mov_b32_e32 v118, v112
	v_mov_b32_e32 v119, v116
	v_mov_b32_e32 v126, v120
	v_mov_b32_e32 v127, v124
	v_mov_b32_e32 v100, v129
	v_mov_b32_e32 v108, v105
	v_mov_b32_e32 v116, v113
	v_mov_b32_e32 v124, v121
	v_add_u32_e32 v8, 16, v8
	s_waitcnt vmcnt(48)
	v_mov_b32_e32 v66, v166
	v_mov_b32_e32 v130, v167
	v_mov_b32_e32 v138, v168
	v_mov_b32_e32 v140, v169
	v_pk_fma_f32 v[4:5], v[66:67], v[142:143], v[4:5] op_sel_hi:[0,1,1]
	v_pk_fma_f32 v[68:69], v[66:67], v[144:145], v[68:69] op_sel_hi:[0,1,1]
	v_pk_fma_f32 v[70:71], v[66:67], v[146:147], v[70:71] op_sel_hi:[0,1,1]
	v_pk_fma_f32 v[72:73], v[66:67], v[148:149], v[72:73] op_sel_hi:[0,1,1]
	v_fmac_f32_e32 v23, v66, v134
	v_pk_fma_f32 v[4:5], v[130:131], v[98:99], v[4:5] op_sel_hi:[0,1,1]
	v_pk_fma_f32 v[68:69], v[130:131], v[106:107], v[68:69] op_sel_hi:[0,1,1]
	v_pk_fma_f32 v[70:71], v[130:131], v[114:115], v[70:71] op_sel_hi:[0,1,1]
	v_pk_fma_f32 v[72:73], v[130:131], v[122:123], v[72:73] op_sel_hi:[0,1,1]
	v_fmac_f32_e32 v23, v130, v135
	v_pk_fma_f32 v[4:5], v[138:139], v[102:103], v[4:5] op_sel_hi:[0,1,1]
	v_pk_fma_f32 v[68:69], v[138:139], v[110:111], v[68:69] op_sel_hi:[0,1,1]
	v_pk_fma_f32 v[70:71], v[138:139], v[118:119], v[70:71] op_sel_hi:[0,1,1]
	v_pk_fma_f32 v[72:73], v[138:139], v[126:127], v[72:73] op_sel_hi:[0,1,1]
	v_fmac_f32_e32 v23, v138, v136
	v_pk_fma_f32 v[4:5], v[140:141], v[100:101], v[4:5] op_sel_hi:[0,1,1]
	v_pk_fma_f32 v[68:69], v[140:141], v[108:109], v[68:69] op_sel_hi:[0,1,1]
	v_pk_fma_f32 v[70:71], v[140:141], v[116:117], v[70:71] op_sel_hi:[0,1,1]
	v_pk_fma_f32 v[72:73], v[140:141], v[124:125], v[72:73] op_sel_hi:[0,1,1]
	v_fmac_f32_e32 v23, v140, v137
	ds_read_b128 v[98:101], v8 offset:4096
	ds_read_b128 v[102:105], v8 offset:8192
	ds_read_b128 v[106:109], v8 offset:12288
	ds_read_b128 v[110:113], v8 offset:16384
	ds_read_b128 v[114:117], v8 offset:20480
	ds_read_b128 v[118:121], v8 offset:24576
	ds_read_b128 v[122:125], v8 offset:28672
	ds_read_b128 v[126:129], v8
	ds_read_b128 v[134:137], v8 offset:32768
	s_waitcnt lgkmcnt(0)
	v_mov_b32_e32 v143, v98
	v_mov_b32_e32 v144, v102
	v_mov_b32_e32 v145, v106
	v_mov_b32_e32 v142, v126
	v_mov_b32_e32 v146, v110
	v_mov_b32_e32 v147, v114
	v_mov_b32_e32 v148, v118
	v_mov_b32_e32 v149, v122
	v_mov_b32_e32 v98, v127
	v_mov_b32_e32 v106, v103
	v_mov_b32_e32 v114, v111
	v_mov_b32_e32 v122, v119
	v_mov_b32_e32 v102, v128
	v_mov_b32_e32 v103, v100
	v_mov_b32_e32 v110, v104
	v_mov_b32_e32 v111, v108
	v_mov_b32_e32 v118, v112
	v_mov_b32_e32 v119, v116
	v_mov_b32_e32 v126, v120
	v_mov_b32_e32 v127, v124
	v_mov_b32_e32 v100, v129
	v_mov_b32_e32 v108, v105
	v_mov_b32_e32 v116, v113
	v_mov_b32_e32 v124, v121
	v_add_u32_e32 v8, 16, v8
	s_waitcnt vmcnt(44)
	v_mov_b32_e32 v66, v170
	v_mov_b32_e32 v130, v171
	v_mov_b32_e32 v138, v172
	v_mov_b32_e32 v140, v173
	v_pk_fma_f32 v[4:5], v[66:67], v[142:143], v[4:5] op_sel_hi:[0,1,1]
	v_pk_fma_f32 v[68:69], v[66:67], v[144:145], v[68:69] op_sel_hi:[0,1,1]
	v_pk_fma_f32 v[70:71], v[66:67], v[146:147], v[70:71] op_sel_hi:[0,1,1]
	v_pk_fma_f32 v[72:73], v[66:67], v[148:149], v[72:73] op_sel_hi:[0,1,1]
	v_fmac_f32_e32 v23, v66, v134
	v_pk_fma_f32 v[4:5], v[130:131], v[98:99], v[4:5] op_sel_hi:[0,1,1]
	v_pk_fma_f32 v[68:69], v[130:131], v[106:107], v[68:69] op_sel_hi:[0,1,1]
	v_pk_fma_f32 v[70:71], v[130:131], v[114:115], v[70:71] op_sel_hi:[0,1,1]
	v_pk_fma_f32 v[72:73], v[130:131], v[122:123], v[72:73] op_sel_hi:[0,1,1]
	v_fmac_f32_e32 v23, v130, v135
	v_pk_fma_f32 v[4:5], v[138:139], v[102:103], v[4:5] op_sel_hi:[0,1,1]
	v_pk_fma_f32 v[68:69], v[138:139], v[110:111], v[68:69] op_sel_hi:[0,1,1]
	v_pk_fma_f32 v[70:71], v[138:139], v[118:119], v[70:71] op_sel_hi:[0,1,1]
	v_pk_fma_f32 v[72:73], v[138:139], v[126:127], v[72:73] op_sel_hi:[0,1,1]
	v_fmac_f32_e32 v23, v138, v136
	v_pk_fma_f32 v[4:5], v[140:141], v[100:101], v[4:5] op_sel_hi:[0,1,1]
	v_pk_fma_f32 v[68:69], v[140:141], v[108:109], v[68:69] op_sel_hi:[0,1,1]
	v_pk_fma_f32 v[70:71], v[140:141], v[116:117], v[70:71] op_sel_hi:[0,1,1]
	v_pk_fma_f32 v[72:73], v[140:141], v[124:125], v[72:73] op_sel_hi:[0,1,1]
	v_fmac_f32_e32 v23, v140, v137
	ds_read_b128 v[98:101], v8 offset:4096
	ds_read_b128 v[102:105], v8 offset:8192
	ds_read_b128 v[106:109], v8 offset:12288
	ds_read_b128 v[110:113], v8 offset:16384
	ds_read_b128 v[114:117], v8 offset:20480
	ds_read_b128 v[118:121], v8 offset:24576
	ds_read_b128 v[122:125], v8 offset:28672
	ds_read_b128 v[126:129], v8
	ds_read_b128 v[134:137], v8 offset:32768
	s_waitcnt lgkmcnt(0)
	v_mov_b32_e32 v143, v98
	v_mov_b32_e32 v144, v102
	v_mov_b32_e32 v145, v106
	v_mov_b32_e32 v142, v126
	v_mov_b32_e32 v146, v110
	v_mov_b32_e32 v147, v114
	v_mov_b32_e32 v148, v118
	v_mov_b32_e32 v149, v122
	v_mov_b32_e32 v98, v127
	v_mov_b32_e32 v106, v103
	v_mov_b32_e32 v114, v111
	v_mov_b32_e32 v122, v119
	v_mov_b32_e32 v102, v128
	v_mov_b32_e32 v103, v100
	v_mov_b32_e32 v110, v104
	v_mov_b32_e32 v111, v108
	v_mov_b32_e32 v118, v112
	v_mov_b32_e32 v119, v116
	v_mov_b32_e32 v126, v120
	v_mov_b32_e32 v127, v124
	v_mov_b32_e32 v100, v129
	v_mov_b32_e32 v108, v105
	v_mov_b32_e32 v116, v113
	v_mov_b32_e32 v124, v121
	v_add_u32_e32 v8, 16, v8
	s_waitcnt vmcnt(40)
	v_mov_b32_e32 v66, v174
	v_mov_b32_e32 v130, v175
	v_mov_b32_e32 v138, v176
	v_mov_b32_e32 v140, v177
	v_pk_fma_f32 v[4:5], v[66:67], v[142:143], v[4:5] op_sel_hi:[0,1,1]
	v_pk_fma_f32 v[68:69], v[66:67], v[144:145], v[68:69] op_sel_hi:[0,1,1]
	v_pk_fma_f32 v[70:71], v[66:67], v[146:147], v[70:71] op_sel_hi:[0,1,1]
	v_pk_fma_f32 v[72:73], v[66:67], v[148:149], v[72:73] op_sel_hi:[0,1,1]
	v_fmac_f32_e32 v23, v66, v134
	v_pk_fma_f32 v[4:5], v[130:131], v[98:99], v[4:5] op_sel_hi:[0,1,1]
	v_pk_fma_f32 v[68:69], v[130:131], v[106:107], v[68:69] op_sel_hi:[0,1,1]
	v_pk_fma_f32 v[70:71], v[130:131], v[114:115], v[70:71] op_sel_hi:[0,1,1]
	v_pk_fma_f32 v[72:73], v[130:131], v[122:123], v[72:73] op_sel_hi:[0,1,1]
	v_fmac_f32_e32 v23, v130, v135
	v_pk_fma_f32 v[4:5], v[138:139], v[102:103], v[4:5] op_sel_hi:[0,1,1]
	v_pk_fma_f32 v[68:69], v[138:139], v[110:111], v[68:69] op_sel_hi:[0,1,1]
	v_pk_fma_f32 v[70:71], v[138:139], v[118:119], v[70:71] op_sel_hi:[0,1,1]
	v_pk_fma_f32 v[72:73], v[138:139], v[126:127], v[72:73] op_sel_hi:[0,1,1]
	v_fmac_f32_e32 v23, v138, v136
	v_pk_fma_f32 v[4:5], v[140:141], v[100:101], v[4:5] op_sel_hi:[0,1,1]
	v_pk_fma_f32 v[68:69], v[140:141], v[108:109], v[68:69] op_sel_hi:[0,1,1]
	v_pk_fma_f32 v[70:71], v[140:141], v[116:117], v[70:71] op_sel_hi:[0,1,1]
	v_pk_fma_f32 v[72:73], v[140:141], v[124:125], v[72:73] op_sel_hi:[0,1,1]
	v_fmac_f32_e32 v23, v140, v137
	ds_read_b128 v[98:101], v8 offset:4096
	ds_read_b128 v[102:105], v8 offset:8192
	ds_read_b128 v[106:109], v8 offset:12288
	ds_read_b128 v[110:113], v8 offset:16384
	ds_read_b128 v[114:117], v8 offset:20480
	ds_read_b128 v[118:121], v8 offset:24576
	ds_read_b128 v[122:125], v8 offset:28672
	ds_read_b128 v[126:129], v8
	ds_read_b128 v[134:137], v8 offset:32768
	s_waitcnt lgkmcnt(0)
	v_mov_b32_e32 v143, v98
	v_mov_b32_e32 v144, v102
	v_mov_b32_e32 v145, v106
	v_mov_b32_e32 v142, v126
	v_mov_b32_e32 v146, v110
	v_mov_b32_e32 v147, v114
	v_mov_b32_e32 v148, v118
	v_mov_b32_e32 v149, v122
	v_mov_b32_e32 v98, v127
	v_mov_b32_e32 v106, v103
	v_mov_b32_e32 v114, v111
	v_mov_b32_e32 v122, v119
	v_mov_b32_e32 v102, v128
	v_mov_b32_e32 v103, v100
	v_mov_b32_e32 v110, v104
	v_mov_b32_e32 v111, v108
	v_mov_b32_e32 v118, v112
	v_mov_b32_e32 v119, v116
	v_mov_b32_e32 v126, v120
	v_mov_b32_e32 v127, v124
	v_mov_b32_e32 v100, v129
	v_mov_b32_e32 v108, v105
	v_mov_b32_e32 v116, v113
	v_mov_b32_e32 v124, v121
	v_add_u32_e32 v8, 16, v8
	s_waitcnt vmcnt(36)
	v_mov_b32_e32 v66, v178
	v_mov_b32_e32 v130, v179
	v_mov_b32_e32 v138, v180
	v_mov_b32_e32 v140, v181
	v_pk_fma_f32 v[4:5], v[66:67], v[142:143], v[4:5] op_sel_hi:[0,1,1]
	v_pk_fma_f32 v[68:69], v[66:67], v[144:145], v[68:69] op_sel_hi:[0,1,1]
	v_pk_fma_f32 v[70:71], v[66:67], v[146:147], v[70:71] op_sel_hi:[0,1,1]
	v_pk_fma_f32 v[72:73], v[66:67], v[148:149], v[72:73] op_sel_hi:[0,1,1]
	v_fmac_f32_e32 v23, v66, v134
	v_pk_fma_f32 v[4:5], v[130:131], v[98:99], v[4:5] op_sel_hi:[0,1,1]
	v_pk_fma_f32 v[68:69], v[130:131], v[106:107], v[68:69] op_sel_hi:[0,1,1]
	v_pk_fma_f32 v[70:71], v[130:131], v[114:115], v[70:71] op_sel_hi:[0,1,1]
	v_pk_fma_f32 v[72:73], v[130:131], v[122:123], v[72:73] op_sel_hi:[0,1,1]
	v_fmac_f32_e32 v23, v130, v135
	v_pk_fma_f32 v[4:5], v[138:139], v[102:103], v[4:5] op_sel_hi:[0,1,1]
	v_pk_fma_f32 v[68:69], v[138:139], v[110:111], v[68:69] op_sel_hi:[0,1,1]
	v_pk_fma_f32 v[70:71], v[138:139], v[118:119], v[70:71] op_sel_hi:[0,1,1]
	v_pk_fma_f32 v[72:73], v[138:139], v[126:127], v[72:73] op_sel_hi:[0,1,1]
	v_fmac_f32_e32 v23, v138, v136
	v_pk_fma_f32 v[4:5], v[140:141], v[100:101], v[4:5] op_sel_hi:[0,1,1]
	v_pk_fma_f32 v[68:69], v[140:141], v[108:109], v[68:69] op_sel_hi:[0,1,1]
	v_pk_fma_f32 v[70:71], v[140:141], v[116:117], v[70:71] op_sel_hi:[0,1,1]
	v_pk_fma_f32 v[72:73], v[140:141], v[124:125], v[72:73] op_sel_hi:[0,1,1]
	v_fmac_f32_e32 v23, v140, v137
	ds_read_b128 v[98:101], v8 offset:4096
	ds_read_b128 v[102:105], v8 offset:8192
	ds_read_b128 v[106:109], v8 offset:12288
	ds_read_b128 v[110:113], v8 offset:16384
	ds_read_b128 v[114:117], v8 offset:20480
	ds_read_b128 v[118:121], v8 offset:24576
	ds_read_b128 v[122:125], v8 offset:28672
	ds_read_b128 v[126:129], v8
	ds_read_b128 v[134:137], v8 offset:32768
	s_waitcnt lgkmcnt(0)
	v_mov_b32_e32 v143, v98
	v_mov_b32_e32 v144, v102
	v_mov_b32_e32 v145, v106
	v_mov_b32_e32 v142, v126
	v_mov_b32_e32 v146, v110
	v_mov_b32_e32 v147, v114
	v_mov_b32_e32 v148, v118
	v_mov_b32_e32 v149, v122
	v_mov_b32_e32 v98, v127
	v_mov_b32_e32 v106, v103
	v_mov_b32_e32 v114, v111
	v_mov_b32_e32 v122, v119
	v_mov_b32_e32 v102, v128
	v_mov_b32_e32 v103, v100
	v_mov_b32_e32 v110, v104
	v_mov_b32_e32 v111, v108
	v_mov_b32_e32 v118, v112
	v_mov_b32_e32 v119, v116
	v_mov_b32_e32 v126, v120
	v_mov_b32_e32 v127, v124
	v_mov_b32_e32 v100, v129
	v_mov_b32_e32 v108, v105
	v_mov_b32_e32 v116, v113
	v_mov_b32_e32 v124, v121
	v_add_u32_e32 v8, 16, v8
	s_waitcnt vmcnt(32)
	v_mov_b32_e32 v66, v182
	v_mov_b32_e32 v130, v183
	v_mov_b32_e32 v138, v184
	v_mov_b32_e32 v140, v185
	v_pk_fma_f32 v[4:5], v[66:67], v[142:143], v[4:5] op_sel_hi:[0,1,1]
	v_pk_fma_f32 v[68:69], v[66:67], v[144:145], v[68:69] op_sel_hi:[0,1,1]
	v_pk_fma_f32 v[70:71], v[66:67], v[146:147], v[70:71] op_sel_hi:[0,1,1]
	v_pk_fma_f32 v[72:73], v[66:67], v[148:149], v[72:73] op_sel_hi:[0,1,1]
	v_fmac_f32_e32 v23, v66, v134
	v_pk_fma_f32 v[4:5], v[130:131], v[98:99], v[4:5] op_sel_hi:[0,1,1]
	v_pk_fma_f32 v[68:69], v[130:131], v[106:107], v[68:69] op_sel_hi:[0,1,1]
	v_pk_fma_f32 v[70:71], v[130:131], v[114:115], v[70:71] op_sel_hi:[0,1,1]
	v_pk_fma_f32 v[72:73], v[130:131], v[122:123], v[72:73] op_sel_hi:[0,1,1]
	v_fmac_f32_e32 v23, v130, v135
	v_pk_fma_f32 v[4:5], v[138:139], v[102:103], v[4:5] op_sel_hi:[0,1,1]
	v_pk_fma_f32 v[68:69], v[138:139], v[110:111], v[68:69] op_sel_hi:[0,1,1]
	v_pk_fma_f32 v[70:71], v[138:139], v[118:119], v[70:71] op_sel_hi:[0,1,1]
	v_pk_fma_f32 v[72:73], v[138:139], v[126:127], v[72:73] op_sel_hi:[0,1,1]
	v_fmac_f32_e32 v23, v138, v136
	v_pk_fma_f32 v[4:5], v[140:141], v[100:101], v[4:5] op_sel_hi:[0,1,1]
	v_pk_fma_f32 v[68:69], v[140:141], v[108:109], v[68:69] op_sel_hi:[0,1,1]
	v_pk_fma_f32 v[70:71], v[140:141], v[116:117], v[70:71] op_sel_hi:[0,1,1]
	v_pk_fma_f32 v[72:73], v[140:141], v[124:125], v[72:73] op_sel_hi:[0,1,1]
	v_fmac_f32_e32 v23, v140, v137
	ds_read_b128 v[98:101], v8 offset:4096
	ds_read_b128 v[102:105], v8 offset:8192
	ds_read_b128 v[106:109], v8 offset:12288
	ds_read_b128 v[110:113], v8 offset:16384
	ds_read_b128 v[114:117], v8 offset:20480
	ds_read_b128 v[118:121], v8 offset:24576
	ds_read_b128 v[122:125], v8 offset:28672
	ds_read_b128 v[126:129], v8
	ds_read_b128 v[134:137], v8 offset:32768
	s_waitcnt lgkmcnt(0)
	v_mov_b32_e32 v143, v98
	v_mov_b32_e32 v144, v102
	v_mov_b32_e32 v145, v106
	v_mov_b32_e32 v142, v126
	v_mov_b32_e32 v146, v110
	v_mov_b32_e32 v147, v114
	v_mov_b32_e32 v148, v118
	v_mov_b32_e32 v149, v122
	v_mov_b32_e32 v98, v127
	v_mov_b32_e32 v106, v103
	v_mov_b32_e32 v114, v111
	v_mov_b32_e32 v122, v119
	v_mov_b32_e32 v102, v128
	v_mov_b32_e32 v103, v100
	v_mov_b32_e32 v110, v104
	v_mov_b32_e32 v111, v108
	v_mov_b32_e32 v118, v112
	v_mov_b32_e32 v119, v116
	v_mov_b32_e32 v126, v120
	v_mov_b32_e32 v127, v124
	v_mov_b32_e32 v100, v129
	v_mov_b32_e32 v108, v105
	v_mov_b32_e32 v116, v113
	v_mov_b32_e32 v124, v121
	v_add_u32_e32 v8, 16, v8
	s_waitcnt vmcnt(28)
	v_mov_b32_e32 v66, v186
	v_mov_b32_e32 v130, v187
	v_mov_b32_e32 v138, v188
	v_mov_b32_e32 v140, v189
	v_pk_fma_f32 v[4:5], v[66:67], v[142:143], v[4:5] op_sel_hi:[0,1,1]
	v_pk_fma_f32 v[68:69], v[66:67], v[144:145], v[68:69] op_sel_hi:[0,1,1]
	v_pk_fma_f32 v[70:71], v[66:67], v[146:147], v[70:71] op_sel_hi:[0,1,1]
	v_pk_fma_f32 v[72:73], v[66:67], v[148:149], v[72:73] op_sel_hi:[0,1,1]
	v_fmac_f32_e32 v23, v66, v134
	v_pk_fma_f32 v[4:5], v[130:131], v[98:99], v[4:5] op_sel_hi:[0,1,1]
	v_pk_fma_f32 v[68:69], v[130:131], v[106:107], v[68:69] op_sel_hi:[0,1,1]
	v_pk_fma_f32 v[70:71], v[130:131], v[114:115], v[70:71] op_sel_hi:[0,1,1]
	v_pk_fma_f32 v[72:73], v[130:131], v[122:123], v[72:73] op_sel_hi:[0,1,1]
	v_fmac_f32_e32 v23, v130, v135
	v_pk_fma_f32 v[4:5], v[138:139], v[102:103], v[4:5] op_sel_hi:[0,1,1]
	v_pk_fma_f32 v[68:69], v[138:139], v[110:111], v[68:69] op_sel_hi:[0,1,1]
	v_pk_fma_f32 v[70:71], v[138:139], v[118:119], v[70:71] op_sel_hi:[0,1,1]
	v_pk_fma_f32 v[72:73], v[138:139], v[126:127], v[72:73] op_sel_hi:[0,1,1]
	v_fmac_f32_e32 v23, v138, v136
	v_pk_fma_f32 v[4:5], v[140:141], v[100:101], v[4:5] op_sel_hi:[0,1,1]
	v_pk_fma_f32 v[68:69], v[140:141], v[108:109], v[68:69] op_sel_hi:[0,1,1]
	v_pk_fma_f32 v[70:71], v[140:141], v[116:117], v[70:71] op_sel_hi:[0,1,1]
	v_pk_fma_f32 v[72:73], v[140:141], v[124:125], v[72:73] op_sel_hi:[0,1,1]
	v_fmac_f32_e32 v23, v140, v137
	ds_read_b128 v[98:101], v8 offset:4096
	ds_read_b128 v[102:105], v8 offset:8192
	ds_read_b128 v[106:109], v8 offset:12288
	ds_read_b128 v[110:113], v8 offset:16384
	ds_read_b128 v[114:117], v8 offset:20480
	ds_read_b128 v[118:121], v8 offset:24576
	ds_read_b128 v[122:125], v8 offset:28672
	ds_read_b128 v[126:129], v8
	ds_read_b128 v[134:137], v8 offset:32768
	s_waitcnt lgkmcnt(0)
	v_mov_b32_e32 v143, v98
	v_mov_b32_e32 v144, v102
	v_mov_b32_e32 v145, v106
	v_mov_b32_e32 v142, v126
	v_mov_b32_e32 v146, v110
	v_mov_b32_e32 v147, v114
	v_mov_b32_e32 v148, v118
	v_mov_b32_e32 v149, v122
	v_mov_b32_e32 v98, v127
	v_mov_b32_e32 v106, v103
	v_mov_b32_e32 v114, v111
	v_mov_b32_e32 v122, v119
	v_mov_b32_e32 v102, v128
	v_mov_b32_e32 v103, v100
	v_mov_b32_e32 v110, v104
	v_mov_b32_e32 v111, v108
	v_mov_b32_e32 v118, v112
	v_mov_b32_e32 v119, v116
	v_mov_b32_e32 v126, v120
	v_mov_b32_e32 v127, v124
	v_mov_b32_e32 v100, v129
	v_mov_b32_e32 v108, v105
	v_mov_b32_e32 v116, v113
	v_mov_b32_e32 v124, v121
	v_add_u32_e32 v8, 16, v8
	s_waitcnt vmcnt(24)
	v_mov_b32_e32 v66, v190
	v_mov_b32_e32 v130, v191
	v_mov_b32_e32 v138, v192
	v_mov_b32_e32 v140, v193
	v_pk_fma_f32 v[4:5], v[66:67], v[142:143], v[4:5] op_sel_hi:[0,1,1]
	v_pk_fma_f32 v[68:69], v[66:67], v[144:145], v[68:69] op_sel_hi:[0,1,1]
	v_pk_fma_f32 v[70:71], v[66:67], v[146:147], v[70:71] op_sel_hi:[0,1,1]
	v_pk_fma_f32 v[72:73], v[66:67], v[148:149], v[72:73] op_sel_hi:[0,1,1]
	v_fmac_f32_e32 v23, v66, v134
	v_pk_fma_f32 v[4:5], v[130:131], v[98:99], v[4:5] op_sel_hi:[0,1,1]
	v_pk_fma_f32 v[68:69], v[130:131], v[106:107], v[68:69] op_sel_hi:[0,1,1]
	v_pk_fma_f32 v[70:71], v[130:131], v[114:115], v[70:71] op_sel_hi:[0,1,1]
	v_pk_fma_f32 v[72:73], v[130:131], v[122:123], v[72:73] op_sel_hi:[0,1,1]
	v_fmac_f32_e32 v23, v130, v135
	v_pk_fma_f32 v[4:5], v[138:139], v[102:103], v[4:5] op_sel_hi:[0,1,1]
	v_pk_fma_f32 v[68:69], v[138:139], v[110:111], v[68:69] op_sel_hi:[0,1,1]
	v_pk_fma_f32 v[70:71], v[138:139], v[118:119], v[70:71] op_sel_hi:[0,1,1]
	v_pk_fma_f32 v[72:73], v[138:139], v[126:127], v[72:73] op_sel_hi:[0,1,1]
	v_fmac_f32_e32 v23, v138, v136
	v_pk_fma_f32 v[4:5], v[140:141], v[100:101], v[4:5] op_sel_hi:[0,1,1]
	v_pk_fma_f32 v[68:69], v[140:141], v[108:109], v[68:69] op_sel_hi:[0,1,1]
	v_pk_fma_f32 v[70:71], v[140:141], v[116:117], v[70:71] op_sel_hi:[0,1,1]
	v_pk_fma_f32 v[72:73], v[140:141], v[124:125], v[72:73] op_sel_hi:[0,1,1]
	v_fmac_f32_e32 v23, v140, v137
	ds_read_b128 v[98:101], v8 offset:4096
	ds_read_b128 v[102:105], v8 offset:8192
	ds_read_b128 v[106:109], v8 offset:12288
	ds_read_b128 v[110:113], v8 offset:16384
	ds_read_b128 v[114:117], v8 offset:20480
	ds_read_b128 v[118:121], v8 offset:24576
	ds_read_b128 v[122:125], v8 offset:28672
	ds_read_b128 v[126:129], v8
	ds_read_b128 v[134:137], v8 offset:32768
	s_waitcnt lgkmcnt(0)
	v_mov_b32_e32 v143, v98
	v_mov_b32_e32 v144, v102
	v_mov_b32_e32 v145, v106
	v_mov_b32_e32 v142, v126
	v_mov_b32_e32 v146, v110
	v_mov_b32_e32 v147, v114
	v_mov_b32_e32 v148, v118
	v_mov_b32_e32 v149, v122
	v_mov_b32_e32 v98, v127
	v_mov_b32_e32 v106, v103
	v_mov_b32_e32 v114, v111
	v_mov_b32_e32 v122, v119
	v_mov_b32_e32 v102, v128
	v_mov_b32_e32 v103, v100
	v_mov_b32_e32 v110, v104
	v_mov_b32_e32 v111, v108
	v_mov_b32_e32 v118, v112
	v_mov_b32_e32 v119, v116
	v_mov_b32_e32 v126, v120
	v_mov_b32_e32 v127, v124
	v_mov_b32_e32 v100, v129
	v_mov_b32_e32 v108, v105
	v_mov_b32_e32 v116, v113
	v_mov_b32_e32 v124, v121
	v_add_u32_e32 v8, 16, v8
	s_waitcnt vmcnt(20)
	v_mov_b32_e32 v66, v194
	v_mov_b32_e32 v130, v195
	v_mov_b32_e32 v138, v196
	v_mov_b32_e32 v140, v197
	v_pk_fma_f32 v[4:5], v[66:67], v[142:143], v[4:5] op_sel_hi:[0,1,1]
	v_pk_fma_f32 v[68:69], v[66:67], v[144:145], v[68:69] op_sel_hi:[0,1,1]
	v_pk_fma_f32 v[70:71], v[66:67], v[146:147], v[70:71] op_sel_hi:[0,1,1]
	v_pk_fma_f32 v[72:73], v[66:67], v[148:149], v[72:73] op_sel_hi:[0,1,1]
	v_fmac_f32_e32 v23, v66, v134
	v_pk_fma_f32 v[4:5], v[130:131], v[98:99], v[4:5] op_sel_hi:[0,1,1]
	v_pk_fma_f32 v[68:69], v[130:131], v[106:107], v[68:69] op_sel_hi:[0,1,1]
	v_pk_fma_f32 v[70:71], v[130:131], v[114:115], v[70:71] op_sel_hi:[0,1,1]
	v_pk_fma_f32 v[72:73], v[130:131], v[122:123], v[72:73] op_sel_hi:[0,1,1]
	v_fmac_f32_e32 v23, v130, v135
	v_pk_fma_f32 v[4:5], v[138:139], v[102:103], v[4:5] op_sel_hi:[0,1,1]
	v_pk_fma_f32 v[68:69], v[138:139], v[110:111], v[68:69] op_sel_hi:[0,1,1]
	v_pk_fma_f32 v[70:71], v[138:139], v[118:119], v[70:71] op_sel_hi:[0,1,1]
	v_pk_fma_f32 v[72:73], v[138:139], v[126:127], v[72:73] op_sel_hi:[0,1,1]
	v_fmac_f32_e32 v23, v138, v136
	v_pk_fma_f32 v[4:5], v[140:141], v[100:101], v[4:5] op_sel_hi:[0,1,1]
	v_pk_fma_f32 v[68:69], v[140:141], v[108:109], v[68:69] op_sel_hi:[0,1,1]
	v_pk_fma_f32 v[70:71], v[140:141], v[116:117], v[70:71] op_sel_hi:[0,1,1]
	v_pk_fma_f32 v[72:73], v[140:141], v[124:125], v[72:73] op_sel_hi:[0,1,1]
	v_fmac_f32_e32 v23, v140, v137
	ds_read_b128 v[98:101], v8 offset:4096
	ds_read_b128 v[102:105], v8 offset:8192
	ds_read_b128 v[106:109], v8 offset:12288
	ds_read_b128 v[110:113], v8 offset:16384
	ds_read_b128 v[114:117], v8 offset:20480
	ds_read_b128 v[118:121], v8 offset:24576
	ds_read_b128 v[122:125], v8 offset:28672
	ds_read_b128 v[126:129], v8
	ds_read_b128 v[134:137], v8 offset:32768
	s_waitcnt lgkmcnt(0)
	v_mov_b32_e32 v143, v98
	v_mov_b32_e32 v144, v102
	v_mov_b32_e32 v145, v106
	v_mov_b32_e32 v142, v126
	v_mov_b32_e32 v146, v110
	v_mov_b32_e32 v147, v114
	v_mov_b32_e32 v148, v118
	v_mov_b32_e32 v149, v122
	v_mov_b32_e32 v98, v127
	v_mov_b32_e32 v106, v103
	v_mov_b32_e32 v114, v111
	v_mov_b32_e32 v122, v119
	v_mov_b32_e32 v102, v128
	v_mov_b32_e32 v103, v100
	v_mov_b32_e32 v110, v104
	v_mov_b32_e32 v111, v108
	v_mov_b32_e32 v118, v112
	v_mov_b32_e32 v119, v116
	v_mov_b32_e32 v126, v120
	v_mov_b32_e32 v127, v124
	v_mov_b32_e32 v100, v129
	v_mov_b32_e32 v108, v105
	v_mov_b32_e32 v116, v113
	v_mov_b32_e32 v124, v121
	v_add_u32_e32 v8, 16, v8
	s_waitcnt vmcnt(16)
	v_mov_b32_e32 v66, v198
	v_mov_b32_e32 v130, v199
	v_mov_b32_e32 v138, v200
	v_mov_b32_e32 v140, v201
	v_pk_fma_f32 v[4:5], v[66:67], v[142:143], v[4:5] op_sel_hi:[0,1,1]
	v_pk_fma_f32 v[68:69], v[66:67], v[144:145], v[68:69] op_sel_hi:[0,1,1]
	v_pk_fma_f32 v[70:71], v[66:67], v[146:147], v[70:71] op_sel_hi:[0,1,1]
	v_pk_fma_f32 v[72:73], v[66:67], v[148:149], v[72:73] op_sel_hi:[0,1,1]
	v_fmac_f32_e32 v23, v66, v134
	v_pk_fma_f32 v[4:5], v[130:131], v[98:99], v[4:5] op_sel_hi:[0,1,1]
	v_pk_fma_f32 v[68:69], v[130:131], v[106:107], v[68:69] op_sel_hi:[0,1,1]
	v_pk_fma_f32 v[70:71], v[130:131], v[114:115], v[70:71] op_sel_hi:[0,1,1]
	v_pk_fma_f32 v[72:73], v[130:131], v[122:123], v[72:73] op_sel_hi:[0,1,1]
	v_fmac_f32_e32 v23, v130, v135
	v_pk_fma_f32 v[4:5], v[138:139], v[102:103], v[4:5] op_sel_hi:[0,1,1]
	v_pk_fma_f32 v[68:69], v[138:139], v[110:111], v[68:69] op_sel_hi:[0,1,1]
	v_pk_fma_f32 v[70:71], v[138:139], v[118:119], v[70:71] op_sel_hi:[0,1,1]
	v_pk_fma_f32 v[72:73], v[138:139], v[126:127], v[72:73] op_sel_hi:[0,1,1]
	v_fmac_f32_e32 v23, v138, v136
	v_pk_fma_f32 v[4:5], v[140:141], v[100:101], v[4:5] op_sel_hi:[0,1,1]
	v_pk_fma_f32 v[68:69], v[140:141], v[108:109], v[68:69] op_sel_hi:[0,1,1]
	v_pk_fma_f32 v[70:71], v[140:141], v[116:117], v[70:71] op_sel_hi:[0,1,1]
	v_pk_fma_f32 v[72:73], v[140:141], v[124:125], v[72:73] op_sel_hi:[0,1,1]
	v_fmac_f32_e32 v23, v140, v137
	ds_read_b128 v[98:101], v8 offset:4096
	ds_read_b128 v[102:105], v8 offset:8192
	ds_read_b128 v[106:109], v8 offset:12288
	ds_read_b128 v[110:113], v8 offset:16384
	ds_read_b128 v[114:117], v8 offset:20480
	ds_read_b128 v[118:121], v8 offset:24576
	ds_read_b128 v[122:125], v8 offset:28672
	ds_read_b128 v[126:129], v8
	ds_read_b128 v[134:137], v8 offset:32768
	s_waitcnt lgkmcnt(0)
	v_mov_b32_e32 v143, v98
	v_mov_b32_e32 v144, v102
	v_mov_b32_e32 v145, v106
	v_mov_b32_e32 v142, v126
	v_mov_b32_e32 v146, v110
	v_mov_b32_e32 v147, v114
	v_mov_b32_e32 v148, v118
	v_mov_b32_e32 v149, v122
	v_mov_b32_e32 v98, v127
	v_mov_b32_e32 v106, v103
	v_mov_b32_e32 v114, v111
	v_mov_b32_e32 v122, v119
	v_mov_b32_e32 v102, v128
	v_mov_b32_e32 v103, v100
	v_mov_b32_e32 v110, v104
	v_mov_b32_e32 v111, v108
	v_mov_b32_e32 v118, v112
	v_mov_b32_e32 v119, v116
	v_mov_b32_e32 v126, v120
	v_mov_b32_e32 v127, v124
	v_mov_b32_e32 v100, v129
	v_mov_b32_e32 v108, v105
	v_mov_b32_e32 v116, v113
	v_mov_b32_e32 v124, v121
	v_add_u32_e32 v8, 16, v8
	s_waitcnt vmcnt(12)
	v_mov_b32_e32 v66, v202
	v_mov_b32_e32 v130, v203
	v_mov_b32_e32 v138, v204
	v_mov_b32_e32 v140, v205
	v_pk_fma_f32 v[4:5], v[66:67], v[142:143], v[4:5] op_sel_hi:[0,1,1]
	v_pk_fma_f32 v[68:69], v[66:67], v[144:145], v[68:69] op_sel_hi:[0,1,1]
	v_pk_fma_f32 v[70:71], v[66:67], v[146:147], v[70:71] op_sel_hi:[0,1,1]
	v_pk_fma_f32 v[72:73], v[66:67], v[148:149], v[72:73] op_sel_hi:[0,1,1]
	v_fmac_f32_e32 v23, v66, v134
	v_pk_fma_f32 v[4:5], v[130:131], v[98:99], v[4:5] op_sel_hi:[0,1,1]
	v_pk_fma_f32 v[68:69], v[130:131], v[106:107], v[68:69] op_sel_hi:[0,1,1]
	v_pk_fma_f32 v[70:71], v[130:131], v[114:115], v[70:71] op_sel_hi:[0,1,1]
	v_pk_fma_f32 v[72:73], v[130:131], v[122:123], v[72:73] op_sel_hi:[0,1,1]
	v_fmac_f32_e32 v23, v130, v135
	v_pk_fma_f32 v[4:5], v[138:139], v[102:103], v[4:5] op_sel_hi:[0,1,1]
	v_pk_fma_f32 v[68:69], v[138:139], v[110:111], v[68:69] op_sel_hi:[0,1,1]
	v_pk_fma_f32 v[70:71], v[138:139], v[118:119], v[70:71] op_sel_hi:[0,1,1]
	v_pk_fma_f32 v[72:73], v[138:139], v[126:127], v[72:73] op_sel_hi:[0,1,1]
	v_fmac_f32_e32 v23, v138, v136
	v_pk_fma_f32 v[4:5], v[140:141], v[100:101], v[4:5] op_sel_hi:[0,1,1]
	v_pk_fma_f32 v[68:69], v[140:141], v[108:109], v[68:69] op_sel_hi:[0,1,1]
	v_pk_fma_f32 v[70:71], v[140:141], v[116:117], v[70:71] op_sel_hi:[0,1,1]
	v_pk_fma_f32 v[72:73], v[140:141], v[124:125], v[72:73] op_sel_hi:[0,1,1]
	v_fmac_f32_e32 v23, v140, v137
	ds_read_b128 v[98:101], v8 offset:4096
	ds_read_b128 v[102:105], v8 offset:8192
	ds_read_b128 v[106:109], v8 offset:12288
	ds_read_b128 v[110:113], v8 offset:16384
	ds_read_b128 v[114:117], v8 offset:20480
	ds_read_b128 v[118:121], v8 offset:24576
	ds_read_b128 v[122:125], v8 offset:28672
	ds_read_b128 v[126:129], v8
	ds_read_b128 v[134:137], v8 offset:32768
	s_waitcnt lgkmcnt(0)
	v_mov_b32_e32 v143, v98
	v_mov_b32_e32 v144, v102
	v_mov_b32_e32 v145, v106
	v_mov_b32_e32 v142, v126
	v_mov_b32_e32 v146, v110
	v_mov_b32_e32 v147, v114
	v_mov_b32_e32 v148, v118
	v_mov_b32_e32 v149, v122
	v_mov_b32_e32 v98, v127
	v_mov_b32_e32 v106, v103
	v_mov_b32_e32 v114, v111
	v_mov_b32_e32 v122, v119
	v_mov_b32_e32 v102, v128
	v_mov_b32_e32 v103, v100
	v_mov_b32_e32 v110, v104
	v_mov_b32_e32 v111, v108
	v_mov_b32_e32 v118, v112
	v_mov_b32_e32 v119, v116
	v_mov_b32_e32 v126, v120
	v_mov_b32_e32 v127, v124
	v_mov_b32_e32 v100, v129
	v_mov_b32_e32 v108, v105
	v_mov_b32_e32 v116, v113
	v_mov_b32_e32 v124, v121
	v_add_u32_e32 v8, 16, v8
	s_waitcnt vmcnt(8)
	v_mov_b32_e32 v66, v206
	v_mov_b32_e32 v130, v207
	v_mov_b32_e32 v138, v208
	v_mov_b32_e32 v140, v209
	v_pk_fma_f32 v[4:5], v[66:67], v[142:143], v[4:5] op_sel_hi:[0,1,1]
	v_pk_fma_f32 v[68:69], v[66:67], v[144:145], v[68:69] op_sel_hi:[0,1,1]
	v_pk_fma_f32 v[70:71], v[66:67], v[146:147], v[70:71] op_sel_hi:[0,1,1]
	v_pk_fma_f32 v[72:73], v[66:67], v[148:149], v[72:73] op_sel_hi:[0,1,1]
	v_fmac_f32_e32 v23, v66, v134
	v_pk_fma_f32 v[4:5], v[130:131], v[98:99], v[4:5] op_sel_hi:[0,1,1]
	v_pk_fma_f32 v[68:69], v[130:131], v[106:107], v[68:69] op_sel_hi:[0,1,1]
	v_pk_fma_f32 v[70:71], v[130:131], v[114:115], v[70:71] op_sel_hi:[0,1,1]
	v_pk_fma_f32 v[72:73], v[130:131], v[122:123], v[72:73] op_sel_hi:[0,1,1]
	v_fmac_f32_e32 v23, v130, v135
	v_pk_fma_f32 v[4:5], v[138:139], v[102:103], v[4:5] op_sel_hi:[0,1,1]
	v_pk_fma_f32 v[68:69], v[138:139], v[110:111], v[68:69] op_sel_hi:[0,1,1]
	v_pk_fma_f32 v[70:71], v[138:139], v[118:119], v[70:71] op_sel_hi:[0,1,1]
	v_pk_fma_f32 v[72:73], v[138:139], v[126:127], v[72:73] op_sel_hi:[0,1,1]
	v_fmac_f32_e32 v23, v138, v136
	v_pk_fma_f32 v[4:5], v[140:141], v[100:101], v[4:5] op_sel_hi:[0,1,1]
	v_pk_fma_f32 v[68:69], v[140:141], v[108:109], v[68:69] op_sel_hi:[0,1,1]
	v_pk_fma_f32 v[70:71], v[140:141], v[116:117], v[70:71] op_sel_hi:[0,1,1]
	v_pk_fma_f32 v[72:73], v[140:141], v[124:125], v[72:73] op_sel_hi:[0,1,1]
	v_fmac_f32_e32 v23, v140, v137
	ds_read_b128 v[98:101], v8 offset:4096
	ds_read_b128 v[102:105], v8 offset:8192
	ds_read_b128 v[106:109], v8 offset:12288
	ds_read_b128 v[110:113], v8 offset:16384
	ds_read_b128 v[114:117], v8 offset:20480
	ds_read_b128 v[118:121], v8 offset:24576
	ds_read_b128 v[122:125], v8 offset:28672
	ds_read_b128 v[126:129], v8
	ds_read_b128 v[134:137], v8 offset:32768
	s_waitcnt lgkmcnt(0)
	v_mov_b32_e32 v143, v98
	v_mov_b32_e32 v144, v102
	v_mov_b32_e32 v145, v106
	v_mov_b32_e32 v142, v126
	v_mov_b32_e32 v146, v110
	v_mov_b32_e32 v147, v114
	v_mov_b32_e32 v148, v118
	v_mov_b32_e32 v149, v122
	v_mov_b32_e32 v98, v127
	v_mov_b32_e32 v106, v103
	v_mov_b32_e32 v114, v111
	v_mov_b32_e32 v122, v119
	v_mov_b32_e32 v102, v128
	v_mov_b32_e32 v103, v100
	v_mov_b32_e32 v110, v104
	v_mov_b32_e32 v111, v108
	v_mov_b32_e32 v118, v112
	v_mov_b32_e32 v119, v116
	v_mov_b32_e32 v126, v120
	v_mov_b32_e32 v127, v124
	v_mov_b32_e32 v100, v129
	v_mov_b32_e32 v108, v105
	v_mov_b32_e32 v116, v113
	v_mov_b32_e32 v124, v121
	v_add_u32_e32 v8, 16, v8
	s_waitcnt vmcnt(4)
	v_mov_b32_e32 v66, v150
	v_mov_b32_e32 v130, v151
	v_mov_b32_e32 v138, v152
	v_mov_b32_e32 v140, v153
	v_pk_fma_f32 v[4:5], v[66:67], v[142:143], v[4:5] op_sel_hi:[0,1,1]
	v_pk_fma_f32 v[68:69], v[66:67], v[144:145], v[68:69] op_sel_hi:[0,1,1]
	v_pk_fma_f32 v[70:71], v[66:67], v[146:147], v[70:71] op_sel_hi:[0,1,1]
	v_pk_fma_f32 v[72:73], v[66:67], v[148:149], v[72:73] op_sel_hi:[0,1,1]
	v_fmac_f32_e32 v23, v66, v134
	v_pk_fma_f32 v[4:5], v[130:131], v[98:99], v[4:5] op_sel_hi:[0,1,1]
	v_pk_fma_f32 v[68:69], v[130:131], v[106:107], v[68:69] op_sel_hi:[0,1,1]
	v_pk_fma_f32 v[70:71], v[130:131], v[114:115], v[70:71] op_sel_hi:[0,1,1]
	v_pk_fma_f32 v[72:73], v[130:131], v[122:123], v[72:73] op_sel_hi:[0,1,1]
	v_fmac_f32_e32 v23, v130, v135
	v_pk_fma_f32 v[4:5], v[138:139], v[102:103], v[4:5] op_sel_hi:[0,1,1]
	v_pk_fma_f32 v[68:69], v[138:139], v[110:111], v[68:69] op_sel_hi:[0,1,1]
	v_pk_fma_f32 v[70:71], v[138:139], v[118:119], v[70:71] op_sel_hi:[0,1,1]
	v_pk_fma_f32 v[72:73], v[138:139], v[126:127], v[72:73] op_sel_hi:[0,1,1]
	v_fmac_f32_e32 v23, v138, v136
	v_pk_fma_f32 v[4:5], v[140:141], v[100:101], v[4:5] op_sel_hi:[0,1,1]
	v_pk_fma_f32 v[68:69], v[140:141], v[108:109], v[68:69] op_sel_hi:[0,1,1]
	v_pk_fma_f32 v[70:71], v[140:141], v[116:117], v[70:71] op_sel_hi:[0,1,1]
	v_pk_fma_f32 v[72:73], v[140:141], v[124:125], v[72:73] op_sel_hi:[0,1,1]
	v_fmac_f32_e32 v23, v140, v137
	ds_read_b128 v[98:101], v8 offset:4096
	ds_read_b128 v[102:105], v8 offset:8192
	ds_read_b128 v[106:109], v8 offset:12288
	ds_read_b128 v[110:113], v8 offset:16384
	ds_read_b128 v[114:117], v8 offset:20480
	ds_read_b128 v[118:121], v8 offset:24576
	ds_read_b128 v[122:125], v8 offset:28672
	ds_read_b128 v[126:129], v8
	ds_read_b128 v[134:137], v8 offset:32768
	s_waitcnt lgkmcnt(0)
	v_mov_b32_e32 v143, v98
	v_mov_b32_e32 v144, v102
	v_mov_b32_e32 v145, v106
	v_mov_b32_e32 v142, v126
	v_mov_b32_e32 v146, v110
	v_mov_b32_e32 v147, v114
	v_mov_b32_e32 v148, v118
	v_mov_b32_e32 v149, v122
	v_mov_b32_e32 v98, v127
	v_mov_b32_e32 v106, v103
	v_mov_b32_e32 v114, v111
	v_mov_b32_e32 v122, v119
	v_mov_b32_e32 v102, v128
	v_mov_b32_e32 v103, v100
	v_mov_b32_e32 v110, v104
	v_mov_b32_e32 v111, v108
	v_mov_b32_e32 v118, v112
	v_mov_b32_e32 v119, v116
	v_mov_b32_e32 v126, v120
	v_mov_b32_e32 v127, v124
	v_mov_b32_e32 v100, v129
	v_mov_b32_e32 v108, v105
	v_mov_b32_e32 v116, v113
	v_mov_b32_e32 v124, v121
	v_add_u32_e32 v8, 16, v8
	s_waitcnt vmcnt(0)
	v_mov_b32_e32 v66, v154
	v_mov_b32_e32 v130, v155
	v_mov_b32_e32 v138, v156
	v_mov_b32_e32 v140, v157
	v_pk_fma_f32 v[4:5], v[66:67], v[142:143], v[4:5] op_sel_hi:[0,1,1]
	v_pk_fma_f32 v[68:69], v[66:67], v[144:145], v[68:69] op_sel_hi:[0,1,1]
	v_pk_fma_f32 v[70:71], v[66:67], v[146:147], v[70:71] op_sel_hi:[0,1,1]
	v_pk_fma_f32 v[72:73], v[66:67], v[148:149], v[72:73] op_sel_hi:[0,1,1]
	v_fmac_f32_e32 v23, v66, v134
	v_pk_fma_f32 v[4:5], v[130:131], v[98:99], v[4:5] op_sel_hi:[0,1,1]
	v_pk_fma_f32 v[68:69], v[130:131], v[106:107], v[68:69] op_sel_hi:[0,1,1]
	v_pk_fma_f32 v[70:71], v[130:131], v[114:115], v[70:71] op_sel_hi:[0,1,1]
	v_pk_fma_f32 v[72:73], v[130:131], v[122:123], v[72:73] op_sel_hi:[0,1,1]
	v_fmac_f32_e32 v23, v130, v135
	v_pk_fma_f32 v[4:5], v[138:139], v[102:103], v[4:5] op_sel_hi:[0,1,1]
	v_pk_fma_f32 v[68:69], v[138:139], v[110:111], v[68:69] op_sel_hi:[0,1,1]
	v_pk_fma_f32 v[70:71], v[138:139], v[118:119], v[70:71] op_sel_hi:[0,1,1]
	v_pk_fma_f32 v[72:73], v[138:139], v[126:127], v[72:73] op_sel_hi:[0,1,1]
	v_fmac_f32_e32 v23, v138, v136
	v_pk_fma_f32 v[4:5], v[140:141], v[100:101], v[4:5] op_sel_hi:[0,1,1]
	v_pk_fma_f32 v[68:69], v[140:141], v[108:109], v[68:69] op_sel_hi:[0,1,1]
	v_pk_fma_f32 v[70:71], v[140:141], v[116:117], v[70:71] op_sel_hi:[0,1,1]
	v_pk_fma_f32 v[72:73], v[140:141], v[124:125], v[72:73] op_sel_hi:[0,1,1]
	v_fmac_f32_e32 v23, v140, v137
	v_add_u32_e32 v2, 0x9000, v76
	ds_write2_b32 v2, v4, v5 offset1:32
	ds_write2_b32 v2, v68, v69 offset0:64 offset1:96
	ds_write2_b32 v2, v70, v71 offset0:128 offset1:160
	ds_write2_b32 v2, v72, v73 offset0:192 offset1:224
	ds_write_b32 v76, v23 offset:37888
	v_mov_b32_e32 v2, s63
	v_mov_b32_e32 v4, s75
	s_waitcnt lgkmcnt(0)
	s_barrier
	ds_read_b64 v[2:3], v2
	ds_read_b64 v[4:5], v4
	v_lshl_or_b32 v8, v1, 5, v74
	v_add_u32_e32 v8, 0xfffdd800, v8
	s_mov_b64 s[52:53], 0
	s_waitcnt lgkmcnt(1)
	v_lshl_add_u64 v[2:3], v[2:3], 0, s[36:37]
	s_waitcnt lgkmcnt(0)
	v_lshl_add_u64 v[4:5], v[8:9], 2, v[4:5]
	v_mov_b32_e32 v8, v84
	v_mov_b32_e32 v23, v83
	v_mov_b32_e32 v61, v82
	v_mov_b32_e32 v65, v89
